# GEMM K-loops: LDS-DMA addresses as scalar base + 32-bit lane offset (saddr form) instead of a 64-bit VALU add per DMA (8 loops x 16 adds removed)
# speedup vs baseline: 1.0029x; 1.0029x over previous
; #define PG8_STAGE(bufoff, gbase, voff) do { _Pragma("unroll") for (int _i = 0; _i < 2; ++_i) \
;         __builtin_amdgcn_global_load_lds((const unsigned*)((const char*)(gbase) + (voff)[_i]), (LAS unsigned*)(lds + (bufoff) + ldsw + _i * 8192), 16, 0, 0); } while (0)
; #define PG8_LDA(dst, b, h) do { _Pragma("unroll") for (int m = 0; m < 4; ++m) _Pragma("unroll") for (int k = 0; k < 2; ++k) dst[m][k] = *(const LAS bf16x8*)(lds + PG8_SA(b, h) + aoff + m * 2048 + k * 1024); } while (0)
; #define PG8_LDB(dst, b, h) do { _Pragma("unroll") for (int n = 0; n < 2; ++n) _Pragma("unroll") for (int k = 0; k < 2; ++k) dst[n][k] = *(const LAS bf16x8*)(lds + PG8_SB(b, h) + boff + n * 2048 + k * 1024); } while (0)
; #define PG8_MMA(ai, bj, At, Bt) do { __builtin_amdgcn_s_setprio(1); _Pragma("unroll") for (int m = 0; m < 4; ++m) _Pragma("unroll") for (int n = 0; n < 2; ++n) _Pragma("unroll") for (int k = 0; k < 2; ++k) \
;         acc[ai][bj][m][n] = __builtin_amdgcn_mfma_f32_16x16x32_bf16(Bt[n][k], At[m][k], acc[ai][bj][m][n], 0, 0, 0); __builtin_amdgcn_s_setprio(0); } while (0)
; template <class Epi, bool ALIGN_EPI, int K, int LDA, int LDB>
; __device__ __forceinline__ void gemm_phase(LAS unsigned char* lds, const int wid, const Gemm g, const StaticOrder& S, const Epi& E) {
;     ...
;         for (int t = 0; t < nt; t += 2) {
;             const bool last = (t == nt - 2);
;             const char* a1 = cA + (size_t)(t + 1) * kstep;
;             const char* a2 = last ? nA : cA + (size_t)(t + 2) * kstep; const char* b2 = last ? nB : cB + (size_t)(t + 2) * kstep;
;             const char* a3 = a2 + kstep; const char* b3 = b2 + kstep;
;             PG8_LDB(B0, 0, 0); PG8_LDB(B1, 0, 1); PG8_SCHED; PG8_LDA(At, 0, 0); PG8_STAGE(PG8_SA(1, 1), a1 + hA, voffA);
;             PG8_WAIT_V(8); PG8_WAIT_L(0); PG8_BAR; PG8_MMA(0, 0, At, B0); PG8_MMA(0, 1, At, B1); PG8_BAR; PG8_SCHED;
;             PG8_LDA(At, 0, 1); PG8_STAGE(PG8_SB(0, 0), b2, voffB); PG8_STAGE(PG8_SB(0, 1), b2 + hB, voffB); PG8_STAGE(PG8_SA(0, 0), a2, voffA);
;             PG8_WAIT_V(8); PG8_WAIT_L(0); PG8_BAR; PG8_MMA(1, 0, At, B0); PG8_MMA(1, 1, At, B1); PG8_BAR; PG8_SCHED;
;             PG8_LDB(B0, 1, 0); PG8_LDB(B1, 1, 1); PG8_SCHED; PG8_LDA(At, 1, 0); PG8_STAGE(PG8_SA(0, 1), a2 + hA, voffA);
;             PG8_WAIT_V(8); PG8_WAIT_L(0); PG8_BAR; PG8_MMA(0, 0, At, B0); PG8_MMA(0, 1, At, B1); PG8_BAR; PG8_SCHED;
.LBB0_232:
	ds_read_b128 v[148:151], v145
	ds_read_b128 v[152:155], v145 offset:1024
	ds_read_b128 v[156:159], v145 offset:2048
	ds_read_b128 v[160:163], v145 offset:3072
	ds_read_b128 v[164:167], v146
	ds_read_b128 v[168:171], v146 offset:1024
	ds_read_b128 v[172:175], v146 offset:2048
	ds_read_b128 v[176:179], v146 offset:3072
	s_add_u32 s24, s22, 0xfffc0080
	s_addc_u32 s25, s23, -1
	s_cmp_eq_u32 s55, 12
	s_cselect_b32 s27, s17, s25
	s_cselect_b32 s26, s48, s24
	s_cselect_b32 s25, s15, s54
	s_cselect_b32 s24, s49, s51
	s_add_i32 m0, s13, 0xc000
	ds_read_b128 v[180:183], v147
	ds_read_b128 v[184:187], v147 offset:1024
	ds_read_b128 v[188:191], v147 offset:2048
	ds_read_b128 v[192:195], v147 offset:3072
	ds_read_b128 v[196:199], v147 offset:4096
	ds_read_b128 v[200:203], v147 offset:5120
	ds_read_b128 v[204:207], v147 offset:6144
	ds_read_b128 v[208:211], v147 offset:7168
	global_load_lds_dwordx4 v136, s[22:23]
	s_add_i32 m0, s13, 0xe000
	s_nop 0
	global_load_lds_dwordx4 v138, s[22:23]
	s_waitcnt vmcnt(8)
	s_waitcnt lgkmcnt(0)
	s_barrier
	s_setprio 1
	s_waitcnt lgkmcnt(0)
	v_mfma_f32_16x16x32_bf16 v[124:127], v[148:151], v[180:183], v[124:127]
	v_mfma_f32_16x16x32_bf16 v[120:123], v[156:159], v[180:183], v[120:123]
	v_mfma_f32_16x16x32_bf16 v[116:119], v[148:151], v[188:191], v[116:119]
	v_mfma_f32_16x16x32_bf16 v[112:115], v[156:159], v[188:191], v[112:115]
	v_mfma_f32_16x16x32_bf16 v[100:103], v[148:151], v[196:199], v[100:103]
	v_mfma_f32_16x16x32_bf16 v[96:99], v[156:159], v[196:199], v[96:99]
	v_mfma_f32_16x16x32_bf16 v[84:87], v[148:151], v[204:207], v[84:87]
	v_mfma_f32_16x16x32_bf16 v[80:83], v[156:159], v[204:207], v[80:83]
	v_mfma_f32_16x16x32_bf16 v[124:127], v[152:155], v[184:187], v[124:127]
	v_mfma_f32_16x16x32_bf16 v[120:123], v[160:163], v[184:187], v[120:123]
	v_mfma_f32_16x16x32_bf16 v[116:119], v[152:155], v[192:195], v[116:119]
	v_mfma_f32_16x16x32_bf16 v[112:115], v[160:163], v[192:195], v[112:115]
	v_mfma_f32_16x16x32_bf16 v[100:103], v[152:155], v[200:203], v[100:103]
	v_mfma_f32_16x16x32_bf16 v[96:99], v[160:163], v[200:203], v[96:99]
	v_mfma_f32_16x16x32_bf16 v[84:87], v[152:155], v[208:211], v[84:87]
	v_mfma_f32_16x16x32_bf16 v[80:83], v[160:163], v[208:211], v[80:83]
	s_setprio 0
	s_setprio 1
	v_mfma_f32_16x16x32_bf16 v[108:111], v[164:167], v[180:183], v[108:111]
	v_mfma_f32_16x16x32_bf16 v[104:107], v[172:175], v[180:183], v[104:107]
	v_mfma_f32_16x16x32_bf16 v[92:95], v[164:167], v[188:191], v[92:95]
	v_mfma_f32_16x16x32_bf16 v[88:91], v[172:175], v[188:191], v[88:91]
	v_mfma_f32_16x16x32_bf16 v[76:79], v[164:167], v[196:199], v[76:79]
	v_mfma_f32_16x16x32_bf16 v[72:75], v[172:175], v[196:199], v[72:75]
	v_mfma_f32_16x16x32_bf16 v[68:71], v[164:167], v[204:207], v[68:71]
	v_mfma_f32_16x16x32_bf16 v[64:67], v[172:175], v[204:207], v[64:67]
	v_mfma_f32_16x16x32_bf16 v[108:111], v[168:171], v[184:187], v[108:111]
	v_mfma_f32_16x16x32_bf16 v[104:107], v[176:179], v[184:187], v[104:107]
	v_mfma_f32_16x16x32_bf16 v[92:95], v[168:171], v[192:195], v[92:95]
	v_mfma_f32_16x16x32_bf16 v[88:91], v[176:179], v[192:195], v[88:91]
	v_mfma_f32_16x16x32_bf16 v[76:79], v[168:171], v[200:203], v[76:79]
	v_mfma_f32_16x16x32_bf16 v[72:75], v[176:179], v[200:203], v[72:75]
	v_mfma_f32_16x16x32_bf16 v[68:71], v[168:171], v[208:211], v[68:71]
	v_mfma_f32_16x16x32_bf16 v[64:67], v[176:179], v[208:211], v[64:67]
	s_setprio 0
	s_barrier
	s_add_u32 s98, s24, s10
	s_addc_u32 s99, s25, s11
	s_add_u32 s100, s26, s10
	s_addc_u32 s101, s27, s11
	s_add_i32 s56, s40, s3
	s_mov_b32 m0, s56
	ds_read_b128 v[180:183], v147 offset:16384
	ds_read_b128 v[184:187], v147 offset:17408
	ds_read_b128 v[188:191], v147 offset:18432
	ds_read_b128 v[192:195], v147 offset:19456
	ds_read_b128 v[196:199], v147 offset:20480
	ds_read_b128 v[200:203], v147 offset:21504
	ds_read_b128 v[204:207], v147 offset:22528
	ds_read_b128 v[208:211], v147 offset:23552
	global_load_lds_dwordx4 v132, s[24:25]
	s_add_i32 m0, s56, 0x2000
	s_add_u32 s56, s24, 0x40000
	s_addc_u32 s57, s25, 0
	s_add_i32 s58, s41, s3
	global_load_lds_dwordx4 v128, s[24:25]
	s_mov_b32 m0, s58
	s_nop 0
	global_load_lds_dwordx4 v132, s[56:57]
	s_add_i32 m0, s58, 0x2000
	s_nop 0
	global_load_lds_dwordx4 v128, s[56:57]
	s_mov_b32 m0, s13
	s_nop 0
	global_load_lds_dwordx4 v134, s[26:27]
	s_mov_b32 m0, s30
	s_nop 0
	global_load_lds_dwordx4 v130, s[26:27]
	s_waitcnt vmcnt(8)
	s_waitcnt lgkmcnt(0)
	s_barrier
	s_setprio 1
	s_waitcnt lgkmcnt(0)
	v_mfma_f32_16x16x32_bf16 v[60:63], v[148:151], v[180:183], v[60:63]
	v_mfma_f32_16x16x32_bf16 v[56:59], v[156:159], v[180:183], v[56:59]
	v_mfma_f32_16x16x32_bf16 v[52:55], v[148:151], v[188:191], v[52:55]
	v_mfma_f32_16x16x32_bf16 v[48:51], v[156:159], v[188:191], v[48:51]
	v_mfma_f32_16x16x32_bf16 v[36:39], v[148:151], v[196:199], v[36:39]
	v_mfma_f32_16x16x32_bf16 v[32:35], v[156:159], v[196:199], v[32:35]
	v_mfma_f32_16x16x32_bf16 v[20:23], v[148:151], v[204:207], v[20:23]
	v_mfma_f32_16x16x32_bf16 v[16:19], v[156:159], v[204:207], v[16:19]
	v_mfma_f32_16x16x32_bf16 v[60:63], v[152:155], v[184:187], v[60:63]
	v_mfma_f32_16x16x32_bf16 v[56:59], v[160:163], v[184:187], v[56:59]
	v_mfma_f32_16x16x32_bf16 v[52:55], v[152:155], v[192:195], v[52:55]
	v_mfma_f32_16x16x32_bf16 v[48:51], v[160:163], v[192:195], v[48:51]
	v_mfma_f32_16x16x32_bf16 v[36:39], v[152:155], v[200:203], v[36:39]
	v_mfma_f32_16x16x32_bf16 v[32:35], v[160:163], v[200:203], v[32:35]
	v_mfma_f32_16x16x32_bf16 v[20:23], v[152:155], v[208:211], v[20:23]
	v_mfma_f32_16x16x32_bf16 v[16:19], v[160:163], v[208:211], v[16:19]
	s_setprio 0
	s_setprio 1
	v_mfma_f32_16x16x32_bf16 v[44:47], v[164:167], v[180:183], v[44:47]
	v_mfma_f32_16x16x32_bf16 v[40:43], v[172:175], v[180:183], v[40:43]
	v_mfma_f32_16x16x32_bf16 v[28:31], v[164:167], v[188:191], v[28:31]
	v_mfma_f32_16x16x32_bf16 v[24:27], v[172:175], v[188:191], v[24:27]
	v_mfma_f32_16x16x32_bf16 v[12:15], v[164:167], v[196:199], v[12:15]
	v_mfma_f32_16x16x32_bf16 v[8:11], v[172:175], v[196:199], v[8:11]
	v_mfma_f32_16x16x32_bf16 v[4:7], v[164:167], v[204:207], v[4:7]
	v_mfma_f32_16x16x32_bf16 v[0:3], v[172:175], v[204:207], v[0:3]
	v_mfma_f32_16x16x32_bf16 v[44:47], v[168:171], v[184:187], v[44:47]
	v_mfma_f32_16x16x32_bf16 v[40:43], v[176:179], v[184:187], v[40:43]
	v_mfma_f32_16x16x32_bf16 v[28:31], v[168:171], v[192:195], v[28:31]
	v_mfma_f32_16x16x32_bf16 v[24:27], v[176:179], v[192:195], v[24:27]
	v_mfma_f32_16x16x32_bf16 v[12:15], v[168:171], v[200:203], v[12:15]
	v_mfma_f32_16x16x32_bf16 v[8:11], v[176:179], v[200:203], v[8:11]
	v_mfma_f32_16x16x32_bf16 v[4:7], v[168:171], v[208:211], v[4:7]
	v_mfma_f32_16x16x32_bf16 v[0:3], v[176:179], v[208:211], v[0:3]
	s_setprio 0
	s_barrier
; #define PG8_STAGE(bufoff, gbase, voff) do { _Pragma("unroll") for (int _i = 0; _i < 2; ++_i) \
;         __builtin_amdgcn_global_load_lds((const unsigned*)((const char*)(gbase) + (voff)[_i]), (LAS unsigned*)(lds + (bufoff) + ldsw + _i * 8192), 16, 0, 0); } while (0)
; #define PG8_LDA(dst, b, h) do { _Pragma("unroll") for (int m = 0; m < 4; ++m) _Pragma("unroll") for (int k = 0; k < 2; ++k) dst[m][k] = *(const LAS bf16x8*)(lds + PG8_SA(b, h) + aoff + m * 2048 + k * 1024); } while (0)
; #define PG8_LDB(dst, b, h) do { _Pragma("unroll") for (int n = 0; n < 2; ++n) _Pragma("unroll") for (int k = 0; k < 2; ++k) dst[n][k] = *(const LAS bf16x8*)(lds + PG8_SB(b, h) + boff + n * 2048 + k * 1024); } while (0)
; #define PG8_MMA(ai, bj, At, Bt) do { __builtin_amdgcn_s_setprio(1); _Pragma("unroll") for (int m = 0; m < 4; ++m) _Pragma("unroll") for (int n = 0; n < 2; ++n) _Pragma("unroll") for (int k = 0; k < 2; ++k) \
;         acc[ai][bj][m][n] = __builtin_amdgcn_mfma_f32_16x16x32_bf16(Bt[n][k], At[m][k], acc[ai][bj][m][n], 0, 0, 0); __builtin_amdgcn_s_setprio(0); } while (0)
; #define PG8_WAIT_V(n) asm volatile("s_waitcnt vmcnt(" #n ")" ::: "memory")
; #define PG8_WAIT_L(n) asm volatile("s_waitcnt lgkmcnt(" #n ")" ::: "memory")
; #define PG8_BAR __builtin_amdgcn_s_barrier()
; #define PG8_SCHED __builtin_amdgcn_sched_barrier(0)
; template <class Epi, bool ALIGN_EPI, int K, int LDA, int LDB>
; __device__ __forceinline__ void gemm_phase(LAS unsigned char* lds, const int wid, const Gemm g, const StaticOrder& S, const Epi& E) {
;     ...
;             PG8_LDB(B0, 1, 0); PG8_LDB(B1, 1, 1); PG8_SCHED; PG8_LDA(At, 1, 0); PG8_STAGE(PG8_SA(0, 1), a2 + hA, voffA);
;             PG8_WAIT_V(8); PG8_WAIT_L(0); PG8_BAR; PG8_MMA(0, 0, At, B0); PG8_MMA(0, 1, At, B1); PG8_BAR; PG8_SCHED;
;             PG8_LDA(At, 1, 1); PG8_STAGE(PG8_SB(1, 0), b3, voffB); PG8_STAGE(PG8_SB(1, 1), b3 + hB, voffB); PG8_STAGE(PG8_SA(1, 0), a3, voffA);
;             PG8_WAIT_V(8); PG8_WAIT_L(0); PG8_BAR; PG8_MMA(1, 0, At, B0); PG8_MMA(1, 1, At, B1); PG8_BAR; PG8_SCHED;
;         }
;         if constexpr (ALIGN_EPI) { if (wr == 0) PG8_BAR; }
	s_add_i32 s56, 0, 0x18000
	s_add_i32 s57, 0, 0x1c000
	v_add_u32_e32 v160, s56, v144
	v_add_u32_e32 v176, s57, v144
	ds_read_b128 v[148:151], v160
	ds_read_b128 v[152:155], v160 offset:1024
	ds_read_b128 v[156:159], v160 offset:2048
	ds_read_b128 v[160:163], v160 offset:3072
	ds_read_b128 v[164:167], v176
	ds_read_b128 v[168:171], v176 offset:1024
	ds_read_b128 v[172:175], v176 offset:2048
	ds_read_b128 v[176:179], v176 offset:3072
	s_add_u32 s26, s26, 0x40000
	s_addc_u32 s27, s27, 0
	s_mov_b32 m0, s31
	ds_read_b128 v[180:183], v147 offset:32768
	ds_read_b128 v[184:187], v147 offset:33792
	ds_read_b128 v[188:191], v147 offset:34816
	ds_read_b128 v[192:195], v147 offset:35840
	ds_read_b128 v[196:199], v147 offset:36864
	ds_read_b128 v[200:203], v147 offset:37888
	ds_read_b128 v[204:207], v147 offset:38912
	ds_read_b128 v[208:211], v147 offset:39936
	global_load_lds_dwordx4 v134, s[26:27]
	s_mov_b32 m0, s33
	s_nop 0
	global_load_lds_dwordx4 v130, s[26:27]
	s_waitcnt vmcnt(8)
	s_waitcnt lgkmcnt(0)
	s_barrier
	s_setprio 1
	s_waitcnt lgkmcnt(0)
	v_mfma_f32_16x16x32_bf16 v[124:127], v[148:151], v[180:183], v[124:127]
	v_mfma_f32_16x16x32_bf16 v[120:123], v[156:159], v[180:183], v[120:123]
	v_mfma_f32_16x16x32_bf16 v[116:119], v[148:151], v[188:191], v[116:119]
	v_mfma_f32_16x16x32_bf16 v[112:115], v[156:159], v[188:191], v[112:115]
	v_mfma_f32_16x16x32_bf16 v[100:103], v[148:151], v[196:199], v[100:103]
	v_mfma_f32_16x16x32_bf16 v[96:99], v[156:159], v[196:199], v[96:99]
	v_mfma_f32_16x16x32_bf16 v[84:87], v[148:151], v[204:207], v[84:87]
	v_mfma_f32_16x16x32_bf16 v[80:83], v[156:159], v[204:207], v[80:83]
	v_mfma_f32_16x16x32_bf16 v[124:127], v[152:155], v[184:187], v[124:127]
	v_mfma_f32_16x16x32_bf16 v[120:123], v[160:163], v[184:187], v[120:123]
	v_mfma_f32_16x16x32_bf16 v[116:119], v[152:155], v[192:195], v[116:119]
	v_mfma_f32_16x16x32_bf16 v[112:115], v[160:163], v[192:195], v[112:115]
	v_mfma_f32_16x16x32_bf16 v[100:103], v[152:155], v[200:203], v[100:103]
	v_mfma_f32_16x16x32_bf16 v[96:99], v[160:163], v[200:203], v[96:99]
	v_mfma_f32_16x16x32_bf16 v[84:87], v[152:155], v[208:211], v[84:87]
	v_mfma_f32_16x16x32_bf16 v[80:83], v[160:163], v[208:211], v[80:83]
	s_setprio 0
	s_setprio 1
	v_mfma_f32_16x16x32_bf16 v[108:111], v[164:167], v[180:183], v[108:111]
	v_mfma_f32_16x16x32_bf16 v[104:107], v[172:175], v[180:183], v[104:107]
	v_mfma_f32_16x16x32_bf16 v[92:95], v[164:167], v[188:191], v[92:95]
	v_mfma_f32_16x16x32_bf16 v[88:91], v[172:175], v[188:191], v[88:91]
	v_mfma_f32_16x16x32_bf16 v[76:79], v[164:167], v[196:199], v[76:79]
	v_mfma_f32_16x16x32_bf16 v[72:75], v[172:175], v[196:199], v[72:75]
	v_mfma_f32_16x16x32_bf16 v[68:71], v[164:167], v[204:207], v[68:71]
	v_mfma_f32_16x16x32_bf16 v[64:67], v[172:175], v[204:207], v[64:67]
	v_mfma_f32_16x16x32_bf16 v[108:111], v[168:171], v[184:187], v[108:111]
	v_mfma_f32_16x16x32_bf16 v[104:107], v[176:179], v[184:187], v[104:107]
	v_mfma_f32_16x16x32_bf16 v[92:95], v[168:171], v[192:195], v[92:95]
	v_mfma_f32_16x16x32_bf16 v[88:91], v[176:179], v[192:195], v[88:91]
	v_mfma_f32_16x16x32_bf16 v[76:79], v[168:171], v[200:203], v[76:79]
	v_mfma_f32_16x16x32_bf16 v[72:75], v[176:179], v[200:203], v[72:75]
	v_mfma_f32_16x16x32_bf16 v[68:71], v[168:171], v[208:211], v[68:71]
	v_mfma_f32_16x16x32_bf16 v[64:67], v[176:179], v[208:211], v[64:67]
	s_setprio 0
	s_barrier
	s_add_i32 s26, s56, s3
	s_mov_b32 m0, s26
	ds_read_b128 v[180:183], v147 offset:49152
	ds_read_b128 v[184:187], v147 offset:50176
	ds_read_b128 v[188:191], v147 offset:51200
	ds_read_b128 v[192:195], v147 offset:52224
	ds_read_b128 v[196:199], v147 offset:53248
	ds_read_b128 v[200:203], v147 offset:54272
	ds_read_b128 v[204:207], v147 offset:55296
	ds_read_b128 v[208:211], v147 offset:56320
	global_load_lds_dwordx4 v132, s[98:99]
	s_add_i32 m0, s26, 0x2000
	s_add_u32 s24, s24, 0x40080
	s_addc_u32 s25, s25, 0
	s_add_i32 s26, s57, s3
	global_load_lds_dwordx4 v128, s[98:99]
	s_mov_b32 m0, s26
	s_nop 0
	global_load_lds_dwordx4 v132, s[24:25]
	s_add_i32 m0, s26, 0x2000
	s_nop 0
	global_load_lds_dwordx4 v128, s[24:25]
	s_mov_b32 m0, s38
	s_nop 0
	global_load_lds_dwordx4 v134, s[100:101]
	s_mov_b32 m0, s39
	s_nop 0
	global_load_lds_dwordx4 v130, s[100:101]
	s_waitcnt vmcnt(8)
	s_waitcnt lgkmcnt(0)
	s_barrier
	s_setprio 1
	s_waitcnt lgkmcnt(0)
	v_mfma_f32_16x16x32_bf16 v[60:63], v[148:151], v[180:183], v[60:63]
	v_mfma_f32_16x16x32_bf16 v[56:59], v[156:159], v[180:183], v[56:59]
	v_mfma_f32_16x16x32_bf16 v[52:55], v[148:151], v[188:191], v[52:55]
	v_mfma_f32_16x16x32_bf16 v[48:51], v[156:159], v[188:191], v[48:51]
	v_mfma_f32_16x16x32_bf16 v[36:39], v[148:151], v[196:199], v[36:39]
	v_mfma_f32_16x16x32_bf16 v[32:35], v[156:159], v[196:199], v[32:35]
	v_mfma_f32_16x16x32_bf16 v[20:23], v[148:151], v[204:207], v[20:23]
	v_mfma_f32_16x16x32_bf16 v[16:19], v[156:159], v[204:207], v[16:19]
	v_mfma_f32_16x16x32_bf16 v[60:63], v[152:155], v[184:187], v[60:63]
	v_mfma_f32_16x16x32_bf16 v[56:59], v[160:163], v[184:187], v[56:59]
	v_mfma_f32_16x16x32_bf16 v[52:55], v[152:155], v[192:195], v[52:55]
	v_mfma_f32_16x16x32_bf16 v[48:51], v[160:163], v[192:195], v[48:51]
	v_mfma_f32_16x16x32_bf16 v[36:39], v[152:155], v[200:203], v[36:39]
	v_mfma_f32_16x16x32_bf16 v[32:35], v[160:163], v[200:203], v[32:35]
	v_mfma_f32_16x16x32_bf16 v[20:23], v[152:155], v[208:211], v[20:23]
	v_mfma_f32_16x16x32_bf16 v[16:19], v[160:163], v[208:211], v[16:19]
	s_setprio 0
	s_setprio 1
	v_mfma_f32_16x16x32_bf16 v[44:47], v[164:167], v[180:183], v[44:47]
	v_mfma_f32_16x16x32_bf16 v[40:43], v[172:175], v[180:183], v[40:43]
	v_mfma_f32_16x16x32_bf16 v[28:31], v[164:167], v[188:191], v[28:31]
	v_mfma_f32_16x16x32_bf16 v[24:27], v[172:175], v[188:191], v[24:27]
	v_mfma_f32_16x16x32_bf16 v[12:15], v[164:167], v[196:199], v[12:15]
	v_mfma_f32_16x16x32_bf16 v[8:11], v[172:175], v[196:199], v[8:11]
	v_mfma_f32_16x16x32_bf16 v[4:7], v[164:167], v[204:207], v[4:7]
	v_mfma_f32_16x16x32_bf16 v[0:3], v[172:175], v[204:207], v[0:3]
	v_mfma_f32_16x16x32_bf16 v[44:47], v[168:171], v[184:187], v[44:47]
	v_mfma_f32_16x16x32_bf16 v[40:43], v[176:179], v[184:187], v[40:43]
	v_mfma_f32_16x16x32_bf16 v[28:31], v[168:171], v[192:195], v[28:31]
	v_mfma_f32_16x16x32_bf16 v[24:27], v[176:179], v[192:195], v[24:27]
	v_mfma_f32_16x16x32_bf16 v[12:15], v[168:171], v[200:203], v[12:15]
	v_mfma_f32_16x16x32_bf16 v[8:11], v[176:179], v[200:203], v[8:11]
	v_mfma_f32_16x16x32_bf16 v[4:7], v[168:171], v[208:211], v[4:7]
	v_mfma_f32_16x16x32_bf16 v[0:3], v[176:179], v[208:211], v[0:3]
	s_setprio 0
	s_barrier
	s_add_i32 s55, s55, 2
	s_add_u32 s22, s22, 0x100
	s_addc_u32 s23, s23, 0
	s_add_u32 s51, s51, 0x100
	s_addc_u32 s54, s54, 0
	s_cmp_gt_u32 s55, 13
	s_cbranch_scc0 .LBB0_232
	s_and_b64 vcc, exec, s[8:9]
	s_cbranch_vccz .LBB0_235
	s_barrier

; #define PG8_STAGE(bufoff, gbase, voff) do { _Pragma("unroll") for (int _i = 0; _i < 2; ++_i) \
;         __builtin_amdgcn_global_load_lds((const unsigned*)((const char*)(gbase) + (voff)[_i]), (LAS unsigned*)(lds + (bufoff) + ldsw + _i * 8192), 16, 0, 0); } while (0)
; #define PG8_LDA(dst, b, h) do { _Pragma("unroll") for (int m = 0; m < 4; ++m) _Pragma("unroll") for (int k = 0; k < 2; ++k) dst[m][k] = *(const LAS bf16x8*)(lds + PG8_SA(b, h) + aoff + m * 2048 + k * 1024); } while (0)
; #define PG8_LDB(dst, b, h) do { _Pragma("unroll") for (int n = 0; n < 2; ++n) _Pragma("unroll") for (int k = 0; k < 2; ++k) dst[n][k] = *(const LAS bf16x8*)(lds + PG8_SB(b, h) + boff + n * 2048 + k * 1024); } while (0)
; #define PG8_MMA(ai, bj, At, Bt) do { __builtin_amdgcn_s_setprio(1); _Pragma("unroll") for (int m = 0; m < 4; ++m) _Pragma("unroll") for (int n = 0; n < 2; ++n) _Pragma("unroll") for (int k = 0; k < 2; ++k) \
;         acc[ai][bj][m][n] = __builtin_amdgcn_mfma_f32_16x16x32_bf16(Bt[n][k], At[m][k], acc[ai][bj][m][n], 0, 0, 0); __builtin_amdgcn_s_setprio(0); } while (0)
; #define PG8_WAIT_V(n) asm volatile("s_waitcnt vmcnt(" #n ")" ::: "memory")
; #define PG8_WAIT_L(n) asm volatile("s_waitcnt lgkmcnt(" #n ")" ::: "memory")
; #define PG8_BAR __builtin_amdgcn_s_barrier()
; #define PG8_SCHED __builtin_amdgcn_sched_barrier(0)
; template <class Epi, bool ALIGN_EPI, int K, int LDA, int LDB>
; __device__ __forceinline__ void gemm_phase(LAS unsigned char* lds, const int wid, const Gemm g, const StaticOrder& S, const Epi& E) {
;     ...
;             const bool last = (t == nt - 2);
;             const char* a1 = cA + (size_t)(t + 1) * kstep;
;             const char* a2 = last ? nA : cA + (size_t)(t + 2) * kstep; const char* b2 = last ? nB : cB + (size_t)(t + 2) * kstep;
;             const char* a3 = a2 + kstep; const char* b3 = b2 + kstep;
;             PG8_LDB(B0, 0, 0); PG8_LDB(B1, 0, 1); PG8_SCHED; PG8_LDA(At, 0, 0); PG8_STAGE(PG8_SA(1, 1), a1 + hA, voffA);
;             PG8_WAIT_V(8); PG8_WAIT_L(0); PG8_BAR; PG8_MMA(0, 0, At, B0); PG8_MMA(0, 1, At, B1); PG8_BAR; PG8_SCHED;
;             PG8_LDA(At, 0, 1); PG8_STAGE(PG8_SB(0, 0), b2, voffB); PG8_STAGE(PG8_SB(0, 1), b2 + hB, voffB); PG8_STAGE(PG8_SA(0, 0), a2, voffA);
;             PG8_WAIT_V(8); PG8_WAIT_L(0); PG8_BAR; PG8_MMA(1, 0, At, B0); PG8_MMA(1, 1, At, B1); PG8_BAR; PG8_SCHED;
.LBB0_917:
	ds_read_b128 v[128:131], v163
	ds_read_b128 v[132:135], v163 offset:1024
	ds_read_b128 v[136:139], v163 offset:2048
	ds_read_b128 v[140:143], v163 offset:3072
	ds_read_b128 v[166:169], v164
	ds_read_b128 v[170:173], v164 offset:1024
	ds_read_b128 v[174:177], v164 offset:2048
	ds_read_b128 v[178:181], v164 offset:3072
	s_add_u32 s38, s36, 0xfffc0080
	s_addc_u32 s39, s37, -1
	s_cmp_eq_u32 s67, 12
	s_cselect_b32 s41, s27, s39
	s_cselect_b32 s40, s63, s38
	s_cselect_b32 s39, s25, s66
	s_cselect_b32 s38, s64, s65
	s_add_i32 m0, s35, 0xc000
	ds_read_b128 v[182:185], v165
	ds_read_b128 v[186:189], v165 offset:1024
	ds_read_b128 v[190:193], v165 offset:2048
	ds_read_b128 v[194:197], v165 offset:3072
	ds_read_b128 v[198:201], v165 offset:4096
	ds_read_b128 v[202:205], v165 offset:5120
	ds_read_b128 v[206:209], v165 offset:6144
	ds_read_b128 v[210:213], v165 offset:7168
	global_load_lds_dwordx4 v152, s[36:37]
	s_add_i32 m0, s35, 0xe000
	s_nop 0
	global_load_lds_dwordx4 v154, s[36:37]
	s_waitcnt vmcnt(8)
	s_waitcnt lgkmcnt(0)
	s_barrier
	s_setprio 1
	s_waitcnt lgkmcnt(0)
	v_mfma_f32_16x16x32_bf16 v[124:127], v[128:131], v[182:185], v[124:127]
	v_mfma_f32_16x16x32_bf16 v[120:123], v[136:139], v[182:185], v[120:123]
	v_mfma_f32_16x16x32_bf16 v[108:111], v[128:131], v[190:193], v[108:111]
	v_mfma_f32_16x16x32_bf16 v[104:107], v[136:139], v[190:193], v[104:107]
	v_mfma_f32_16x16x32_bf16 v[92:95], v[128:131], v[198:201], v[92:95]
	v_mfma_f32_16x16x32_bf16 v[88:91], v[136:139], v[198:201], v[88:91]
	v_mfma_f32_16x16x32_bf16 v[76:79], v[128:131], v[206:209], v[76:79]
	v_mfma_f32_16x16x32_bf16 v[72:75], v[136:139], v[206:209], v[72:75]
	v_mfma_f32_16x16x32_bf16 v[124:127], v[132:135], v[186:189], v[124:127]
	v_mfma_f32_16x16x32_bf16 v[120:123], v[140:143], v[186:189], v[120:123]
	v_mfma_f32_16x16x32_bf16 v[108:111], v[132:135], v[194:197], v[108:111]
	v_mfma_f32_16x16x32_bf16 v[104:107], v[140:143], v[194:197], v[104:107]
	v_mfma_f32_16x16x32_bf16 v[92:95], v[132:135], v[202:205], v[92:95]
	v_mfma_f32_16x16x32_bf16 v[88:91], v[140:143], v[202:205], v[88:91]
	v_mfma_f32_16x16x32_bf16 v[76:79], v[132:135], v[210:213], v[76:79]
	v_mfma_f32_16x16x32_bf16 v[72:75], v[140:143], v[210:213], v[72:75]
	s_setprio 0
	s_setprio 1
	v_mfma_f32_16x16x32_bf16 v[116:119], v[166:169], v[182:185], v[116:119]
	v_mfma_f32_16x16x32_bf16 v[112:115], v[174:177], v[182:185], v[112:115]
	v_mfma_f32_16x16x32_bf16 v[100:103], v[166:169], v[190:193], v[100:103]
	v_mfma_f32_16x16x32_bf16 v[96:99], v[174:177], v[190:193], v[96:99]
	v_mfma_f32_16x16x32_bf16 v[84:87], v[166:169], v[198:201], v[84:87]
	v_mfma_f32_16x16x32_bf16 v[80:83], v[174:177], v[198:201], v[80:83]
	v_mfma_f32_16x16x32_bf16 v[68:71], v[166:169], v[206:209], v[68:71]
	v_mfma_f32_16x16x32_bf16 v[64:67], v[174:177], v[206:209], v[64:67]
	v_mfma_f32_16x16x32_bf16 v[116:119], v[170:173], v[186:189], v[116:119]
	v_mfma_f32_16x16x32_bf16 v[112:115], v[178:181], v[186:189], v[112:115]
	v_mfma_f32_16x16x32_bf16 v[100:103], v[170:173], v[194:197], v[100:103]
	v_mfma_f32_16x16x32_bf16 v[96:99], v[178:181], v[194:197], v[96:99]
	v_mfma_f32_16x16x32_bf16 v[84:87], v[170:173], v[202:205], v[84:87]
	v_mfma_f32_16x16x32_bf16 v[80:83], v[178:181], v[202:205], v[80:83]
	v_mfma_f32_16x16x32_bf16 v[68:71], v[170:173], v[210:213], v[68:71]
	v_mfma_f32_16x16x32_bf16 v[64:67], v[178:181], v[210:213], v[64:67]
	s_setprio 0
	s_barrier
	s_add_u32 s98, s38, s12
	s_addc_u32 s99, s39, s13
	s_add_u32 s100, s40, s12
	s_addc_u32 s101, s41, s13
	s_add_i32 s52, s58, s33
	s_mov_b32 m0, s52
	ds_read_b128 v[182:185], v165 offset:16384
	ds_read_b128 v[186:189], v165 offset:17408
	ds_read_b128 v[190:193], v165 offset:18432
	ds_read_b128 v[194:197], v165 offset:19456
	ds_read_b128 v[198:201], v165 offset:20480
	ds_read_b128 v[202:205], v165 offset:21504
	ds_read_b128 v[206:209], v165 offset:22528
	ds_read_b128 v[210:213], v165 offset:23552
	global_load_lds_dwordx4 v146, s[38:39]
	s_add_i32 m0, s52, 0x2000
	s_add_u32 s68, s38, 0x40000
	s_addc_u32 s69, s39, 0
	s_add_i32 s52, s59, s33
	global_load_lds_dwordx4 v150, s[38:39]
	s_mov_b32 m0, s52
	s_nop 0
	global_load_lds_dwordx4 v146, s[68:69]
	s_add_i32 m0, s52, 0x2000
	s_nop 0
	global_load_lds_dwordx4 v150, s[68:69]
	s_mov_b32 m0, s35
	s_nop 0
	global_load_lds_dwordx4 v144, s[40:41]
	s_mov_b32 m0, s42
	s_nop 0
	global_load_lds_dwordx4 v148, s[40:41]
	s_waitcnt vmcnt(8)
	s_waitcnt lgkmcnt(0)
	s_barrier
	s_setprio 1
	s_waitcnt lgkmcnt(0)
	v_mfma_f32_16x16x32_bf16 v[60:63], v[128:131], v[182:185], v[60:63]
	v_mfma_f32_16x16x32_bf16 v[56:59], v[136:139], v[182:185], v[56:59]
	v_mfma_f32_16x16x32_bf16 v[44:47], v[128:131], v[190:193], v[44:47]
	v_mfma_f32_16x16x32_bf16 v[40:43], v[136:139], v[190:193], v[40:43]
	v_mfma_f32_16x16x32_bf16 v[28:31], v[128:131], v[198:201], v[28:31]
	v_mfma_f32_16x16x32_bf16 v[24:27], v[136:139], v[198:201], v[24:27]
	v_mfma_f32_16x16x32_bf16 v[12:15], v[128:131], v[206:209], v[12:15]
	v_mfma_f32_16x16x32_bf16 v[8:11], v[136:139], v[206:209], v[8:11]
	v_mfma_f32_16x16x32_bf16 v[60:63], v[132:135], v[186:189], v[60:63]
	v_mfma_f32_16x16x32_bf16 v[56:59], v[140:143], v[186:189], v[56:59]
	v_mfma_f32_16x16x32_bf16 v[44:47], v[132:135], v[194:197], v[44:47]
	v_mfma_f32_16x16x32_bf16 v[40:43], v[140:143], v[194:197], v[40:43]
	v_mfma_f32_16x16x32_bf16 v[28:31], v[132:135], v[202:205], v[28:31]
	v_mfma_f32_16x16x32_bf16 v[24:27], v[140:143], v[202:205], v[24:27]
	v_mfma_f32_16x16x32_bf16 v[12:15], v[132:135], v[210:213], v[12:15]
	v_mfma_f32_16x16x32_bf16 v[8:11], v[140:143], v[210:213], v[8:11]
	s_setprio 0
	s_setprio 1
	v_mfma_f32_16x16x32_bf16 v[52:55], v[166:169], v[182:185], v[52:55]
	v_mfma_f32_16x16x32_bf16 v[48:51], v[174:177], v[182:185], v[48:51]
	v_mfma_f32_16x16x32_bf16 v[36:39], v[166:169], v[190:193], v[36:39]
	v_mfma_f32_16x16x32_bf16 v[32:35], v[174:177], v[190:193], v[32:35]
	v_mfma_f32_16x16x32_bf16 v[20:23], v[166:169], v[198:201], v[20:23]
	v_mfma_f32_16x16x32_bf16 v[16:19], v[174:177], v[198:201], v[16:19]
	v_mfma_f32_16x16x32_bf16 v[4:7], v[166:169], v[206:209], v[4:7]
	v_mfma_f32_16x16x32_bf16 v[0:3], v[174:177], v[206:209], v[0:3]
	v_mfma_f32_16x16x32_bf16 v[52:55], v[170:173], v[186:189], v[52:55]
	v_mfma_f32_16x16x32_bf16 v[48:51], v[178:181], v[186:189], v[48:51]
	v_mfma_f32_16x16x32_bf16 v[36:39], v[170:173], v[194:197], v[36:39]
	v_mfma_f32_16x16x32_bf16 v[32:35], v[178:181], v[194:197], v[32:35]
	v_mfma_f32_16x16x32_bf16 v[20:23], v[170:173], v[202:205], v[20:23]
	v_mfma_f32_16x16x32_bf16 v[16:19], v[178:181], v[202:205], v[16:19]
	v_mfma_f32_16x16x32_bf16 v[4:7], v[170:173], v[210:213], v[4:7]
	v_mfma_f32_16x16x32_bf16 v[0:3], v[178:181], v[210:213], v[0:3]
	s_setprio 0
	s_barrier
; #define PG8_STAGE(bufoff, gbase, voff) do { _Pragma("unroll") for (int _i = 0; _i < 2; ++_i) \
;         __builtin_amdgcn_global_load_lds((const unsigned*)((const char*)(gbase) + (voff)[_i]), (LAS unsigned*)(lds + (bufoff) + ldsw + _i * 8192), 16, 0, 0); } while (0)
; #define PG8_LDA(dst, b, h) do { _Pragma("unroll") for (int m = 0; m < 4; ++m) _Pragma("unroll") for (int k = 0; k < 2; ++k) dst[m][k] = *(const LAS bf16x8*)(lds + PG8_SA(b, h) + aoff + m * 2048 + k * 1024); } while (0)
; #define PG8_LDB(dst, b, h) do { _Pragma("unroll") for (int n = 0; n < 2; ++n) _Pragma("unroll") for (int k = 0; k < 2; ++k) dst[n][k] = *(const LAS bf16x8*)(lds + PG8_SB(b, h) + boff + n * 2048 + k * 1024); } while (0)
; #define PG8_MMA(ai, bj, At, Bt) do { __builtin_amdgcn_s_setprio(1); _Pragma("unroll") for (int m = 0; m < 4; ++m) _Pragma("unroll") for (int n = 0; n < 2; ++n) _Pragma("unroll") for (int k = 0; k < 2; ++k) \
;         acc[ai][bj][m][n] = __builtin_amdgcn_mfma_f32_16x16x32_bf16(Bt[n][k], At[m][k], acc[ai][bj][m][n], 0, 0, 0); __builtin_amdgcn_s_setprio(0); } while (0)
; #define PG8_WAIT_V(n) asm volatile("s_waitcnt vmcnt(" #n ")" ::: "memory")
; #define PG8_WAIT_L(n) asm volatile("s_waitcnt lgkmcnt(" #n ")" ::: "memory")
; #define PG8_BAR __builtin_amdgcn_s_barrier()
; #define PG8_SCHED __builtin_amdgcn_sched_barrier(0)
; template <class Epi, bool ALIGN_EPI, int K, int LDA, int LDB>
; __device__ __forceinline__ void gemm_phase(LAS unsigned char* lds, const int wid, const Gemm g, const StaticOrder& S, const Epi& E) {
;     ...
;             PG8_LDB(B0, 1, 0); PG8_LDB(B1, 1, 1); PG8_SCHED; PG8_LDA(At, 1, 0); PG8_STAGE(PG8_SA(0, 1), a2 + hA, voffA);
;             PG8_WAIT_V(8); PG8_WAIT_L(0); PG8_BAR; PG8_MMA(0, 0, At, B0); PG8_MMA(0, 1, At, B1); PG8_BAR; PG8_SCHED;
;             PG8_LDA(At, 1, 1); PG8_STAGE(PG8_SB(1, 0), b3, voffB); PG8_STAGE(PG8_SB(1, 1), b3 + hB, voffB); PG8_STAGE(PG8_SA(1, 0), a3, voffA);
;             PG8_WAIT_V(8); PG8_WAIT_L(0); PG8_BAR; PG8_MMA(1, 0, At, B0); PG8_MMA(1, 1, At, B1); PG8_BAR; PG8_SCHED;
;         }
;         if constexpr (ALIGN_EPI) { if (wr == 0) PG8_BAR; }
	s_add_i32 s52, 0, 0x18000
	s_add_i32 s53, 0, 0x1c000
	v_add_u32_e32 v140, s52, v162
	v_add_u32_e32 v178, s53, v162
	ds_read_b128 v[128:131], v140
	ds_read_b128 v[132:135], v140 offset:1024
	ds_read_b128 v[136:139], v140 offset:2048
	ds_read_b128 v[140:143], v140 offset:3072
	ds_read_b128 v[166:169], v178
	ds_read_b128 v[170:173], v178 offset:1024
	ds_read_b128 v[174:177], v178 offset:2048
	ds_read_b128 v[178:181], v178 offset:3072
	s_add_u32 s40, s40, 0x40000
	s_addc_u32 s41, s41, 0
	s_mov_b32 m0, s43
	ds_read_b128 v[182:185], v165 offset:32768
	ds_read_b128 v[186:189], v165 offset:33792
	ds_read_b128 v[190:193], v165 offset:34816
	ds_read_b128 v[194:197], v165 offset:35840
	ds_read_b128 v[198:201], v165 offset:36864
	ds_read_b128 v[202:205], v165 offset:37888
	ds_read_b128 v[206:209], v165 offset:38912
	ds_read_b128 v[210:213], v165 offset:39936
	global_load_lds_dwordx4 v144, s[40:41]
	s_mov_b32 m0, s48
	s_nop 0
	global_load_lds_dwordx4 v148, s[40:41]
	s_waitcnt vmcnt(8)
	s_waitcnt lgkmcnt(0)
	s_barrier
	s_setprio 1
	s_waitcnt lgkmcnt(0)
	v_mfma_f32_16x16x32_bf16 v[124:127], v[128:131], v[182:185], v[124:127]
	v_mfma_f32_16x16x32_bf16 v[120:123], v[136:139], v[182:185], v[120:123]
	v_mfma_f32_16x16x32_bf16 v[108:111], v[128:131], v[190:193], v[108:111]
	v_mfma_f32_16x16x32_bf16 v[104:107], v[136:139], v[190:193], v[104:107]
	v_mfma_f32_16x16x32_bf16 v[92:95], v[128:131], v[198:201], v[92:95]
	v_mfma_f32_16x16x32_bf16 v[88:91], v[136:139], v[198:201], v[88:91]
	v_mfma_f32_16x16x32_bf16 v[76:79], v[128:131], v[206:209], v[76:79]
	v_mfma_f32_16x16x32_bf16 v[72:75], v[136:139], v[206:209], v[72:75]
	v_mfma_f32_16x16x32_bf16 v[124:127], v[132:135], v[186:189], v[124:127]
	v_mfma_f32_16x16x32_bf16 v[120:123], v[140:143], v[186:189], v[120:123]
	v_mfma_f32_16x16x32_bf16 v[108:111], v[132:135], v[194:197], v[108:111]
	v_mfma_f32_16x16x32_bf16 v[104:107], v[140:143], v[194:197], v[104:107]
	v_mfma_f32_16x16x32_bf16 v[92:95], v[132:135], v[202:205], v[92:95]
	v_mfma_f32_16x16x32_bf16 v[88:91], v[140:143], v[202:205], v[88:91]
	v_mfma_f32_16x16x32_bf16 v[76:79], v[132:135], v[210:213], v[76:79]
	v_mfma_f32_16x16x32_bf16 v[72:75], v[140:143], v[210:213], v[72:75]
	s_setprio 0
	s_setprio 1
	v_mfma_f32_16x16x32_bf16 v[116:119], v[166:169], v[182:185], v[116:119]
	v_mfma_f32_16x16x32_bf16 v[112:115], v[174:177], v[182:185], v[112:115]
	v_mfma_f32_16x16x32_bf16 v[100:103], v[166:169], v[190:193], v[100:103]
	v_mfma_f32_16x16x32_bf16 v[96:99], v[174:177], v[190:193], v[96:99]
	v_mfma_f32_16x16x32_bf16 v[84:87], v[166:169], v[198:201], v[84:87]
	v_mfma_f32_16x16x32_bf16 v[80:83], v[174:177], v[198:201], v[80:83]
	v_mfma_f32_16x16x32_bf16 v[68:71], v[166:169], v[206:209], v[68:71]
	v_mfma_f32_16x16x32_bf16 v[64:67], v[174:177], v[206:209], v[64:67]
	v_mfma_f32_16x16x32_bf16 v[116:119], v[170:173], v[186:189], v[116:119]
	v_mfma_f32_16x16x32_bf16 v[112:115], v[178:181], v[186:189], v[112:115]
	v_mfma_f32_16x16x32_bf16 v[100:103], v[170:173], v[194:197], v[100:103]
	v_mfma_f32_16x16x32_bf16 v[96:99], v[178:181], v[194:197], v[96:99]
	v_mfma_f32_16x16x32_bf16 v[84:87], v[170:173], v[202:205], v[84:87]
	v_mfma_f32_16x16x32_bf16 v[80:83], v[178:181], v[202:205], v[80:83]
	v_mfma_f32_16x16x32_bf16 v[68:71], v[170:173], v[210:213], v[68:71]
	v_mfma_f32_16x16x32_bf16 v[64:67], v[178:181], v[210:213], v[64:67]
	s_setprio 0
	s_barrier
	s_add_i32 s40, s52, s33
	s_mov_b32 m0, s40
	ds_read_b128 v[182:185], v165 offset:49152
	ds_read_b128 v[186:189], v165 offset:50176
	ds_read_b128 v[190:193], v165 offset:51200
	ds_read_b128 v[194:197], v165 offset:52224
	ds_read_b128 v[198:201], v165 offset:53248
	ds_read_b128 v[202:205], v165 offset:54272
	ds_read_b128 v[206:209], v165 offset:55296
	ds_read_b128 v[210:213], v165 offset:56320
	global_load_lds_dwordx4 v146, s[98:99]
	s_add_i32 m0, s40, 0x2000
	s_add_u32 s38, s38, 0x40080
	s_addc_u32 s39, s39, 0
	s_add_i32 s40, s53, s33
	global_load_lds_dwordx4 v150, s[98:99]
	s_mov_b32 m0, s40
	s_nop 0
	global_load_lds_dwordx4 v146, s[38:39]
	s_add_i32 m0, s40, 0x2000
	s_nop 0
	global_load_lds_dwordx4 v150, s[38:39]
	s_mov_b32 m0, s55
	s_nop 0
	global_load_lds_dwordx4 v144, s[100:101]
	s_mov_b32 m0, s56
	s_nop 0
	global_load_lds_dwordx4 v148, s[100:101]
	s_waitcnt vmcnt(8)
	s_waitcnt lgkmcnt(0)
	s_barrier
	s_setprio 1
	s_waitcnt lgkmcnt(0)
	v_mfma_f32_16x16x32_bf16 v[60:63], v[128:131], v[182:185], v[60:63]
	v_mfma_f32_16x16x32_bf16 v[56:59], v[136:139], v[182:185], v[56:59]
	v_mfma_f32_16x16x32_bf16 v[44:47], v[128:131], v[190:193], v[44:47]
	v_mfma_f32_16x16x32_bf16 v[40:43], v[136:139], v[190:193], v[40:43]
	v_mfma_f32_16x16x32_bf16 v[28:31], v[128:131], v[198:201], v[28:31]
	v_mfma_f32_16x16x32_bf16 v[24:27], v[136:139], v[198:201], v[24:27]
	v_mfma_f32_16x16x32_bf16 v[12:15], v[128:131], v[206:209], v[12:15]
	v_mfma_f32_16x16x32_bf16 v[8:11], v[136:139], v[206:209], v[8:11]
	v_mfma_f32_16x16x32_bf16 v[60:63], v[132:135], v[186:189], v[60:63]
	v_mfma_f32_16x16x32_bf16 v[56:59], v[140:143], v[186:189], v[56:59]
	v_mfma_f32_16x16x32_bf16 v[44:47], v[132:135], v[194:197], v[44:47]
	v_mfma_f32_16x16x32_bf16 v[40:43], v[140:143], v[194:197], v[40:43]
	v_mfma_f32_16x16x32_bf16 v[28:31], v[132:135], v[202:205], v[28:31]
	v_mfma_f32_16x16x32_bf16 v[24:27], v[140:143], v[202:205], v[24:27]
	v_mfma_f32_16x16x32_bf16 v[12:15], v[132:135], v[210:213], v[12:15]
	v_mfma_f32_16x16x32_bf16 v[8:11], v[140:143], v[210:213], v[8:11]
	s_setprio 0
	s_setprio 1
	v_mfma_f32_16x16x32_bf16 v[52:55], v[166:169], v[182:185], v[52:55]
	v_mfma_f32_16x16x32_bf16 v[48:51], v[174:177], v[182:185], v[48:51]
	v_mfma_f32_16x16x32_bf16 v[36:39], v[166:169], v[190:193], v[36:39]
	v_mfma_f32_16x16x32_bf16 v[32:35], v[174:177], v[190:193], v[32:35]
	v_mfma_f32_16x16x32_bf16 v[20:23], v[166:169], v[198:201], v[20:23]
	v_mfma_f32_16x16x32_bf16 v[16:19], v[174:177], v[198:201], v[16:19]
	v_mfma_f32_16x16x32_bf16 v[4:7], v[166:169], v[206:209], v[4:7]
	v_mfma_f32_16x16x32_bf16 v[0:3], v[174:177], v[206:209], v[0:3]
	v_mfma_f32_16x16x32_bf16 v[52:55], v[170:173], v[186:189], v[52:55]
	v_mfma_f32_16x16x32_bf16 v[48:51], v[178:181], v[186:189], v[48:51]
	v_mfma_f32_16x16x32_bf16 v[36:39], v[170:173], v[194:197], v[36:39]
	v_mfma_f32_16x16x32_bf16 v[32:35], v[178:181], v[194:197], v[32:35]
	v_mfma_f32_16x16x32_bf16 v[20:23], v[170:173], v[202:205], v[20:23]
	v_mfma_f32_16x16x32_bf16 v[16:19], v[178:181], v[202:205], v[16:19]
	v_mfma_f32_16x16x32_bf16 v[4:7], v[170:173], v[210:213], v[4:7]
	v_mfma_f32_16x16x32_bf16 v[0:3], v[178:181], v[210:213], v[0:3]
	s_setprio 0
	s_barrier
	s_add_i32 s67, s67, 2
	s_add_u32 s36, s36, 0x100
	s_addc_u32 s37, s37, 0
	s_add_u32 s65, s65, 0x100
	s_addc_u32 s66, s66, 0
	s_cmp_gt_u32 s67, 13
	s_cbranch_scc0 .LBB0_917
	s_and_b64 vcc, exec, s[14:15]
	s_cbranch_vccz .LBB0_920
	s_barrier

; #define PG8_STAGE(bufoff, gbase, voff) do { _Pragma("unroll") for (int _i = 0; _i < 2; ++_i) \
;         __builtin_amdgcn_global_load_lds((const unsigned*)((const char*)(gbase) + (voff)[_i]), (LAS unsigned*)(lds + (bufoff) + ldsw + _i * 8192), 16, 0, 0); } while (0)
; #define PG8_LDA(dst, b, h) do { _Pragma("unroll") for (int m = 0; m < 4; ++m) _Pragma("unroll") for (int k = 0; k < 2; ++k) dst[m][k] = *(const LAS bf16x8*)(lds + PG8_SA(b, h) + aoff + m * 2048 + k * 1024); } while (0)
; #define PG8_LDB(dst, b, h) do { _Pragma("unroll") for (int n = 0; n < 2; ++n) _Pragma("unroll") for (int k = 0; k < 2; ++k) dst[n][k] = *(const LAS bf16x8*)(lds + PG8_SB(b, h) + boff + n * 2048 + k * 1024); } while (0)
; #define PG8_MMA(ai, bj, At, Bt) do { __builtin_amdgcn_s_setprio(1); _Pragma("unroll") for (int m = 0; m < 4; ++m) _Pragma("unroll") for (int n = 0; n < 2; ++n) _Pragma("unroll") for (int k = 0; k < 2; ++k) \
;         acc[ai][bj][m][n] = __builtin_amdgcn_mfma_f32_16x16x32_bf16(Bt[n][k], At[m][k], acc[ai][bj][m][n], 0, 0, 0); __builtin_amdgcn_s_setprio(0); } while (0)
; #define PG8_WAIT_V(n) asm volatile("s_waitcnt vmcnt(" #n ")" ::: "memory")
; #define PG8_WAIT_L(n) asm volatile("s_waitcnt lgkmcnt(" #n ")" ::: "memory")
; #define PG8_BAR __builtin_amdgcn_s_barrier()
; #define PG8_SCHED __builtin_amdgcn_sched_barrier(0)
; template <class Epi, bool ALIGN_EPI, int K, int LDA, int LDB>
; __device__ __forceinline__ void gemm_phase(LAS unsigned char* lds, const int wid, const Gemm g, const StaticOrder& S, const Epi& E) {
;     ...
;             const bool last = (t == nt - 2);
;             const char* a1 = cA + (size_t)(t + 1) * kstep;
;             const char* a2 = last ? nA : cA + (size_t)(t + 2) * kstep; const char* b2 = last ? nB : cB + (size_t)(t + 2) * kstep;
;             const char* a3 = a2 + kstep; const char* b3 = b2 + kstep;
;             PG8_LDB(B0, 0, 0); PG8_LDB(B1, 0, 1); PG8_SCHED; PG8_LDA(At, 0, 0); PG8_STAGE(PG8_SA(1, 1), a1 + hA, voffA);
;             PG8_WAIT_V(8); PG8_WAIT_L(0); PG8_BAR; PG8_MMA(0, 0, At, B0); PG8_MMA(0, 1, At, B1); PG8_BAR; PG8_SCHED;
;             PG8_LDA(At, 0, 1); PG8_STAGE(PG8_SB(0, 0), b2, voffB); PG8_STAGE(PG8_SB(0, 1), b2 + hB, voffB); PG8_STAGE(PG8_SA(0, 0), a2, voffA);
;             PG8_WAIT_V(8); PG8_WAIT_L(0); PG8_BAR; PG8_MMA(1, 0, At, B0); PG8_MMA(1, 1, At, B1); PG8_BAR; PG8_SCHED;
.LBB0_1052:
	ds_read_b128 v[148:151], v145
	ds_read_b128 v[152:155], v145 offset:1024
	ds_read_b128 v[156:159], v145 offset:2048
	ds_read_b128 v[160:163], v145 offset:3072
	ds_read_b128 v[164:167], v146
	ds_read_b128 v[168:171], v146 offset:1024
	ds_read_b128 v[172:175], v146 offset:2048
	ds_read_b128 v[176:179], v146 offset:3072
	s_add_u32 s24, s22, 0xfffc0080
	s_addc_u32 s25, s23, -1
	s_cmp_eq_u32 s55, 12
	s_cselect_b32 s27, s15, s25
	s_cselect_b32 s26, s48, s24
	s_cselect_b32 s25, s13, s54
	s_cselect_b32 s24, s49, s51
	s_add_i32 m0, s21, 0xc000
	ds_read_b128 v[180:183], v147
	ds_read_b128 v[184:187], v147 offset:1024
	ds_read_b128 v[188:191], v147 offset:2048
	ds_read_b128 v[192:195], v147 offset:3072
	ds_read_b128 v[196:199], v147 offset:4096
	ds_read_b128 v[200:203], v147 offset:5120
	ds_read_b128 v[204:207], v147 offset:6144
	ds_read_b128 v[208:211], v147 offset:7168
	global_load_lds_dwordx4 v136, s[22:23]
	s_add_i32 m0, s21, 0xe000
	s_nop 0
	global_load_lds_dwordx4 v138, s[22:23]
	s_waitcnt vmcnt(8)
	s_waitcnt lgkmcnt(0)
	s_barrier
	s_setprio 1
	s_waitcnt lgkmcnt(0)
	v_mfma_f32_16x16x32_bf16 v[124:127], v[148:151], v[180:183], v[124:127]
	v_mfma_f32_16x16x32_bf16 v[120:123], v[156:159], v[180:183], v[120:123]
	v_mfma_f32_16x16x32_bf16 v[108:111], v[148:151], v[188:191], v[108:111]
	v_mfma_f32_16x16x32_bf16 v[104:107], v[156:159], v[188:191], v[104:107]
	v_mfma_f32_16x16x32_bf16 v[92:95], v[148:151], v[196:199], v[92:95]
	v_mfma_f32_16x16x32_bf16 v[88:91], v[156:159], v[196:199], v[88:91]
	v_mfma_f32_16x16x32_bf16 v[76:79], v[148:151], v[204:207], v[76:79]
	v_mfma_f32_16x16x32_bf16 v[72:75], v[156:159], v[204:207], v[72:75]
	v_mfma_f32_16x16x32_bf16 v[124:127], v[152:155], v[184:187], v[124:127]
	v_mfma_f32_16x16x32_bf16 v[120:123], v[160:163], v[184:187], v[120:123]
	v_mfma_f32_16x16x32_bf16 v[108:111], v[152:155], v[192:195], v[108:111]
	v_mfma_f32_16x16x32_bf16 v[104:107], v[160:163], v[192:195], v[104:107]
	v_mfma_f32_16x16x32_bf16 v[92:95], v[152:155], v[200:203], v[92:95]
	v_mfma_f32_16x16x32_bf16 v[88:91], v[160:163], v[200:203], v[88:91]
	v_mfma_f32_16x16x32_bf16 v[76:79], v[152:155], v[208:211], v[76:79]
	v_mfma_f32_16x16x32_bf16 v[72:75], v[160:163], v[208:211], v[72:75]
	s_setprio 0
	s_setprio 1
	v_mfma_f32_16x16x32_bf16 v[116:119], v[164:167], v[180:183], v[116:119]
	v_mfma_f32_16x16x32_bf16 v[112:115], v[172:175], v[180:183], v[112:115]
	v_mfma_f32_16x16x32_bf16 v[100:103], v[164:167], v[188:191], v[100:103]
	v_mfma_f32_16x16x32_bf16 v[96:99], v[172:175], v[188:191], v[96:99]
	v_mfma_f32_16x16x32_bf16 v[84:87], v[164:167], v[196:199], v[84:87]
	v_mfma_f32_16x16x32_bf16 v[80:83], v[172:175], v[196:199], v[80:83]
	v_mfma_f32_16x16x32_bf16 v[68:71], v[164:167], v[204:207], v[68:71]
	v_mfma_f32_16x16x32_bf16 v[64:67], v[172:175], v[204:207], v[64:67]
	v_mfma_f32_16x16x32_bf16 v[116:119], v[168:171], v[184:187], v[116:119]
	v_mfma_f32_16x16x32_bf16 v[112:115], v[176:179], v[184:187], v[112:115]
	v_mfma_f32_16x16x32_bf16 v[100:103], v[168:171], v[192:195], v[100:103]
	v_mfma_f32_16x16x32_bf16 v[96:99], v[176:179], v[192:195], v[96:99]
	v_mfma_f32_16x16x32_bf16 v[84:87], v[168:171], v[200:203], v[84:87]
	v_mfma_f32_16x16x32_bf16 v[80:83], v[176:179], v[200:203], v[80:83]
	v_mfma_f32_16x16x32_bf16 v[68:71], v[168:171], v[208:211], v[68:71]
	v_mfma_f32_16x16x32_bf16 v[64:67], v[176:179], v[208:211], v[64:67]
	s_setprio 0
	s_barrier
	s_add_u32 s98, s24, s10
	s_addc_u32 s99, s25, s11
	s_add_u32 s100, s26, s10
	s_addc_u32 s101, s27, s11
	s_add_i32 s52, s40, s3
	s_mov_b32 m0, s52
	ds_read_b128 v[180:183], v147 offset:16384
	ds_read_b128 v[184:187], v147 offset:17408
	ds_read_b128 v[188:191], v147 offset:18432
	ds_read_b128 v[192:195], v147 offset:19456
	ds_read_b128 v[196:199], v147 offset:20480
	ds_read_b128 v[200:203], v147 offset:21504
	ds_read_b128 v[204:207], v147 offset:22528
	ds_read_b128 v[208:211], v147 offset:23552
	global_load_lds_dwordx4 v132, s[24:25]
	s_add_i32 m0, s52, 0x2000
	s_add_u32 s56, s24, 0x40000
	s_addc_u32 s57, s25, 0
	s_add_i32 s52, s41, s3
	global_load_lds_dwordx4 v128, s[24:25]
	s_mov_b32 m0, s52
	s_nop 0
	global_load_lds_dwordx4 v132, s[56:57]
	s_add_i32 m0, s52, 0x2000
	s_nop 0
	global_load_lds_dwordx4 v128, s[56:57]
	s_mov_b32 m0, s21
	s_nop 0
	global_load_lds_dwordx4 v134, s[26:27]
	s_mov_b32 m0, s30
	s_nop 0
	global_load_lds_dwordx4 v130, s[26:27]
	s_waitcnt vmcnt(8)
	s_waitcnt lgkmcnt(0)
	s_barrier
	s_setprio 1
	s_waitcnt lgkmcnt(0)
	v_mfma_f32_16x16x32_bf16 v[60:63], v[148:151], v[180:183], v[60:63]
	v_mfma_f32_16x16x32_bf16 v[56:59], v[156:159], v[180:183], v[56:59]
	v_mfma_f32_16x16x32_bf16 v[44:47], v[148:151], v[188:191], v[44:47]
	v_mfma_f32_16x16x32_bf16 v[40:43], v[156:159], v[188:191], v[40:43]
	v_mfma_f32_16x16x32_bf16 v[28:31], v[148:151], v[196:199], v[28:31]
	v_mfma_f32_16x16x32_bf16 v[24:27], v[156:159], v[196:199], v[24:27]
	v_mfma_f32_16x16x32_bf16 v[12:15], v[148:151], v[204:207], v[12:15]
	v_mfma_f32_16x16x32_bf16 v[8:11], v[156:159], v[204:207], v[8:11]
	v_mfma_f32_16x16x32_bf16 v[60:63], v[152:155], v[184:187], v[60:63]
	v_mfma_f32_16x16x32_bf16 v[56:59], v[160:163], v[184:187], v[56:59]
	v_mfma_f32_16x16x32_bf16 v[44:47], v[152:155], v[192:195], v[44:47]
	v_mfma_f32_16x16x32_bf16 v[40:43], v[160:163], v[192:195], v[40:43]
	v_mfma_f32_16x16x32_bf16 v[28:31], v[152:155], v[200:203], v[28:31]
	v_mfma_f32_16x16x32_bf16 v[24:27], v[160:163], v[200:203], v[24:27]
	v_mfma_f32_16x16x32_bf16 v[12:15], v[152:155], v[208:211], v[12:15]
	v_mfma_f32_16x16x32_bf16 v[8:11], v[160:163], v[208:211], v[8:11]
	s_setprio 0
	s_setprio 1
	v_mfma_f32_16x16x32_bf16 v[52:55], v[164:167], v[180:183], v[52:55]
	v_mfma_f32_16x16x32_bf16 v[48:51], v[172:175], v[180:183], v[48:51]
	v_mfma_f32_16x16x32_bf16 v[36:39], v[164:167], v[188:191], v[36:39]
	v_mfma_f32_16x16x32_bf16 v[32:35], v[172:175], v[188:191], v[32:35]
	v_mfma_f32_16x16x32_bf16 v[20:23], v[164:167], v[196:199], v[20:23]
	v_mfma_f32_16x16x32_bf16 v[16:19], v[172:175], v[196:199], v[16:19]
	v_mfma_f32_16x16x32_bf16 v[4:7], v[164:167], v[204:207], v[4:7]
	v_mfma_f32_16x16x32_bf16 v[0:3], v[172:175], v[204:207], v[0:3]
	v_mfma_f32_16x16x32_bf16 v[52:55], v[168:171], v[184:187], v[52:55]
	v_mfma_f32_16x16x32_bf16 v[48:51], v[176:179], v[184:187], v[48:51]
	v_mfma_f32_16x16x32_bf16 v[36:39], v[168:171], v[192:195], v[36:39]
	v_mfma_f32_16x16x32_bf16 v[32:35], v[176:179], v[192:195], v[32:35]
	v_mfma_f32_16x16x32_bf16 v[20:23], v[168:171], v[200:203], v[20:23]
	v_mfma_f32_16x16x32_bf16 v[16:19], v[176:179], v[200:203], v[16:19]
	v_mfma_f32_16x16x32_bf16 v[4:7], v[168:171], v[208:211], v[4:7]
	v_mfma_f32_16x16x32_bf16 v[0:3], v[176:179], v[208:211], v[0:3]
	s_setprio 0
	s_barrier
; #define PG8_STAGE(bufoff, gbase, voff) do { _Pragma("unroll") for (int _i = 0; _i < 2; ++_i) \
;         __builtin_amdgcn_global_load_lds((const unsigned*)((const char*)(gbase) + (voff)[_i]), (LAS unsigned*)(lds + (bufoff) + ldsw + _i * 8192), 16, 0, 0); } while (0)
; #define PG8_LDA(dst, b, h) do { _Pragma("unroll") for (int m = 0; m < 4; ++m) _Pragma("unroll") for (int k = 0; k < 2; ++k) dst[m][k] = *(const LAS bf16x8*)(lds + PG8_SA(b, h) + aoff + m * 2048 + k * 1024); } while (0)
; #define PG8_LDB(dst, b, h) do { _Pragma("unroll") for (int n = 0; n < 2; ++n) _Pragma("unroll") for (int k = 0; k < 2; ++k) dst[n][k] = *(const LAS bf16x8*)(lds + PG8_SB(b, h) + boff + n * 2048 + k * 1024); } while (0)
; #define PG8_MMA(ai, bj, At, Bt) do { __builtin_amdgcn_s_setprio(1); _Pragma("unroll") for (int m = 0; m < 4; ++m) _Pragma("unroll") for (int n = 0; n < 2; ++n) _Pragma("unroll") for (int k = 0; k < 2; ++k) \
;         acc[ai][bj][m][n] = __builtin_amdgcn_mfma_f32_16x16x32_bf16(Bt[n][k], At[m][k], acc[ai][bj][m][n], 0, 0, 0); __builtin_amdgcn_s_setprio(0); } while (0)
; #define PG8_WAIT_V(n) asm volatile("s_waitcnt vmcnt(" #n ")" ::: "memory")
; #define PG8_WAIT_L(n) asm volatile("s_waitcnt lgkmcnt(" #n ")" ::: "memory")
; #define PG8_BAR __builtin_amdgcn_s_barrier()
; #define PG8_SCHED __builtin_amdgcn_sched_barrier(0)
; template <class Epi, bool ALIGN_EPI, int K, int LDA, int LDB>
; __device__ __forceinline__ void gemm_phase(LAS unsigned char* lds, const int wid, const Gemm g, const StaticOrder& S, const Epi& E) {
;     ...
;             PG8_LDB(B0, 1, 0); PG8_LDB(B1, 1, 1); PG8_SCHED; PG8_LDA(At, 1, 0); PG8_STAGE(PG8_SA(0, 1), a2 + hA, voffA);
;             PG8_WAIT_V(8); PG8_WAIT_L(0); PG8_BAR; PG8_MMA(0, 0, At, B0); PG8_MMA(0, 1, At, B1); PG8_BAR; PG8_SCHED;
;             PG8_LDA(At, 1, 1); PG8_STAGE(PG8_SB(1, 0), b3, voffB); PG8_STAGE(PG8_SB(1, 1), b3 + hB, voffB); PG8_STAGE(PG8_SA(1, 0), a3, voffA);
;             PG8_WAIT_V(8); PG8_WAIT_L(0); PG8_BAR; PG8_MMA(1, 0, At, B0); PG8_MMA(1, 1, At, B1); PG8_BAR; PG8_SCHED;
;         }
;         if constexpr (ALIGN_EPI) { if (wr == 0) PG8_BAR; }
	s_add_i32 s52, 0, 0x18000
	s_add_i32 s53, 0, 0x1c000
	v_add_u32_e32 v160, s52, v144
	v_add_u32_e32 v176, s53, v144
	ds_read_b128 v[148:151], v160
	ds_read_b128 v[152:155], v160 offset:1024
	ds_read_b128 v[156:159], v160 offset:2048
	ds_read_b128 v[160:163], v160 offset:3072
	ds_read_b128 v[164:167], v176
	ds_read_b128 v[168:171], v176 offset:1024
	ds_read_b128 v[172:175], v176 offset:2048
	ds_read_b128 v[176:179], v176 offset:3072
	s_add_u32 s26, s26, 0x40000
	s_addc_u32 s27, s27, 0
	s_mov_b32 m0, s31
	ds_read_b128 v[180:183], v147 offset:32768
	ds_read_b128 v[184:187], v147 offset:33792
	ds_read_b128 v[188:191], v147 offset:34816
	ds_read_b128 v[192:195], v147 offset:35840
	ds_read_b128 v[196:199], v147 offset:36864
	ds_read_b128 v[200:203], v147 offset:37888
	ds_read_b128 v[204:207], v147 offset:38912
	ds_read_b128 v[208:211], v147 offset:39936
	global_load_lds_dwordx4 v134, s[26:27]
	s_mov_b32 m0, s33
	s_nop 0
	global_load_lds_dwordx4 v130, s[26:27]
	s_waitcnt vmcnt(8)
	s_waitcnt lgkmcnt(0)
	s_barrier
	s_setprio 1
	s_waitcnt lgkmcnt(0)
	v_mfma_f32_16x16x32_bf16 v[124:127], v[148:151], v[180:183], v[124:127]
	v_mfma_f32_16x16x32_bf16 v[120:123], v[156:159], v[180:183], v[120:123]
	v_mfma_f32_16x16x32_bf16 v[108:111], v[148:151], v[188:191], v[108:111]
	v_mfma_f32_16x16x32_bf16 v[104:107], v[156:159], v[188:191], v[104:107]
	v_mfma_f32_16x16x32_bf16 v[92:95], v[148:151], v[196:199], v[92:95]
	v_mfma_f32_16x16x32_bf16 v[88:91], v[156:159], v[196:199], v[88:91]
	v_mfma_f32_16x16x32_bf16 v[76:79], v[148:151], v[204:207], v[76:79]
	v_mfma_f32_16x16x32_bf16 v[72:75], v[156:159], v[204:207], v[72:75]
	v_mfma_f32_16x16x32_bf16 v[124:127], v[152:155], v[184:187], v[124:127]
	v_mfma_f32_16x16x32_bf16 v[120:123], v[160:163], v[184:187], v[120:123]
	v_mfma_f32_16x16x32_bf16 v[108:111], v[152:155], v[192:195], v[108:111]
	v_mfma_f32_16x16x32_bf16 v[104:107], v[160:163], v[192:195], v[104:107]
	v_mfma_f32_16x16x32_bf16 v[92:95], v[152:155], v[200:203], v[92:95]
	v_mfma_f32_16x16x32_bf16 v[88:91], v[160:163], v[200:203], v[88:91]
	v_mfma_f32_16x16x32_bf16 v[76:79], v[152:155], v[208:211], v[76:79]
	v_mfma_f32_16x16x32_bf16 v[72:75], v[160:163], v[208:211], v[72:75]
	s_setprio 0
	s_setprio 1
	v_mfma_f32_16x16x32_bf16 v[116:119], v[164:167], v[180:183], v[116:119]
	v_mfma_f32_16x16x32_bf16 v[112:115], v[172:175], v[180:183], v[112:115]
	v_mfma_f32_16x16x32_bf16 v[100:103], v[164:167], v[188:191], v[100:103]
	v_mfma_f32_16x16x32_bf16 v[96:99], v[172:175], v[188:191], v[96:99]
	v_mfma_f32_16x16x32_bf16 v[84:87], v[164:167], v[196:199], v[84:87]
	v_mfma_f32_16x16x32_bf16 v[80:83], v[172:175], v[196:199], v[80:83]
	v_mfma_f32_16x16x32_bf16 v[68:71], v[164:167], v[204:207], v[68:71]
	v_mfma_f32_16x16x32_bf16 v[64:67], v[172:175], v[204:207], v[64:67]
	v_mfma_f32_16x16x32_bf16 v[116:119], v[168:171], v[184:187], v[116:119]
	v_mfma_f32_16x16x32_bf16 v[112:115], v[176:179], v[184:187], v[112:115]
	v_mfma_f32_16x16x32_bf16 v[100:103], v[168:171], v[192:195], v[100:103]
	v_mfma_f32_16x16x32_bf16 v[96:99], v[176:179], v[192:195], v[96:99]
	v_mfma_f32_16x16x32_bf16 v[84:87], v[168:171], v[200:203], v[84:87]
	v_mfma_f32_16x16x32_bf16 v[80:83], v[176:179], v[200:203], v[80:83]
	v_mfma_f32_16x16x32_bf16 v[68:71], v[168:171], v[208:211], v[68:71]
	v_mfma_f32_16x16x32_bf16 v[64:67], v[176:179], v[208:211], v[64:67]
	s_setprio 0
	s_barrier
	s_add_i32 s26, s52, s3
	s_mov_b32 m0, s26
	ds_read_b128 v[180:183], v147 offset:49152
	ds_read_b128 v[184:187], v147 offset:50176
	ds_read_b128 v[188:191], v147 offset:51200
	ds_read_b128 v[192:195], v147 offset:52224
	ds_read_b128 v[196:199], v147 offset:53248
	ds_read_b128 v[200:203], v147 offset:54272
	ds_read_b128 v[204:207], v147 offset:55296
	ds_read_b128 v[208:211], v147 offset:56320
	global_load_lds_dwordx4 v132, s[98:99]
	s_add_i32 m0, s26, 0x2000
	s_add_u32 s24, s24, 0x40080
	s_addc_u32 s25, s25, 0
	s_add_i32 s26, s53, s3
	global_load_lds_dwordx4 v128, s[98:99]
	s_mov_b32 m0, s26
	s_nop 0
	global_load_lds_dwordx4 v132, s[24:25]
	s_add_i32 m0, s26, 0x2000
	s_nop 0
	global_load_lds_dwordx4 v128, s[24:25]
	s_mov_b32 m0, s38
	s_nop 0
	global_load_lds_dwordx4 v134, s[100:101]
	s_mov_b32 m0, s39
	s_nop 0
	global_load_lds_dwordx4 v130, s[100:101]
	s_waitcnt vmcnt(8)
	s_waitcnt lgkmcnt(0)
	s_barrier
	s_setprio 1
	s_waitcnt lgkmcnt(0)
	v_mfma_f32_16x16x32_bf16 v[60:63], v[148:151], v[180:183], v[60:63]
	v_mfma_f32_16x16x32_bf16 v[56:59], v[156:159], v[180:183], v[56:59]
	v_mfma_f32_16x16x32_bf16 v[44:47], v[148:151], v[188:191], v[44:47]
	v_mfma_f32_16x16x32_bf16 v[40:43], v[156:159], v[188:191], v[40:43]
	v_mfma_f32_16x16x32_bf16 v[28:31], v[148:151], v[196:199], v[28:31]
	v_mfma_f32_16x16x32_bf16 v[24:27], v[156:159], v[196:199], v[24:27]
	v_mfma_f32_16x16x32_bf16 v[12:15], v[148:151], v[204:207], v[12:15]
	v_mfma_f32_16x16x32_bf16 v[8:11], v[156:159], v[204:207], v[8:11]
	v_mfma_f32_16x16x32_bf16 v[60:63], v[152:155], v[184:187], v[60:63]
	v_mfma_f32_16x16x32_bf16 v[56:59], v[160:163], v[184:187], v[56:59]
	v_mfma_f32_16x16x32_bf16 v[44:47], v[152:155], v[192:195], v[44:47]
	v_mfma_f32_16x16x32_bf16 v[40:43], v[160:163], v[192:195], v[40:43]
	v_mfma_f32_16x16x32_bf16 v[28:31], v[152:155], v[200:203], v[28:31]
	v_mfma_f32_16x16x32_bf16 v[24:27], v[160:163], v[200:203], v[24:27]
	v_mfma_f32_16x16x32_bf16 v[12:15], v[152:155], v[208:211], v[12:15]
	v_mfma_f32_16x16x32_bf16 v[8:11], v[160:163], v[208:211], v[8:11]
	s_setprio 0
	s_setprio 1
	v_mfma_f32_16x16x32_bf16 v[52:55], v[164:167], v[180:183], v[52:55]
	v_mfma_f32_16x16x32_bf16 v[48:51], v[172:175], v[180:183], v[48:51]
	v_mfma_f32_16x16x32_bf16 v[36:39], v[164:167], v[188:191], v[36:39]
	v_mfma_f32_16x16x32_bf16 v[32:35], v[172:175], v[188:191], v[32:35]
	v_mfma_f32_16x16x32_bf16 v[20:23], v[164:167], v[196:199], v[20:23]
	v_mfma_f32_16x16x32_bf16 v[16:19], v[172:175], v[196:199], v[16:19]
	v_mfma_f32_16x16x32_bf16 v[4:7], v[164:167], v[204:207], v[4:7]
	v_mfma_f32_16x16x32_bf16 v[0:3], v[172:175], v[204:207], v[0:3]
	v_mfma_f32_16x16x32_bf16 v[52:55], v[168:171], v[184:187], v[52:55]
	v_mfma_f32_16x16x32_bf16 v[48:51], v[176:179], v[184:187], v[48:51]
	v_mfma_f32_16x16x32_bf16 v[36:39], v[168:171], v[192:195], v[36:39]
	v_mfma_f32_16x16x32_bf16 v[32:35], v[176:179], v[192:195], v[32:35]
	v_mfma_f32_16x16x32_bf16 v[20:23], v[168:171], v[200:203], v[20:23]
	v_mfma_f32_16x16x32_bf16 v[16:19], v[176:179], v[200:203], v[16:19]
	v_mfma_f32_16x16x32_bf16 v[4:7], v[168:171], v[208:211], v[4:7]
	v_mfma_f32_16x16x32_bf16 v[0:3], v[176:179], v[208:211], v[0:3]
	s_setprio 0
	s_barrier
	s_add_i32 s55, s55, 2
	s_add_u32 s22, s22, 0x100
	s_addc_u32 s23, s23, 0
	s_add_u32 s51, s51, 0x100
	s_addc_u32 s54, s54, 0
	s_cmp_gt_u32 s55, 13
	s_cbranch_scc0 .LBB0_1052
	s_and_b64 vcc, exec, s[8:9]
	s_cbranch_vccz .LBB0_1055
	s_barrier

; #define PG8_STAGE(bufoff, gbase, voff) do { _Pragma("unroll") for (int _i = 0; _i < 2; ++_i) \
;         __builtin_amdgcn_global_load_lds((const unsigned*)((const char*)(gbase) + (voff)[_i]), (LAS unsigned*)(lds + (bufoff) + ldsw + _i * 8192), 16, 0, 0); } while (0)
; #define PG8_LDA(dst, b, h) do { _Pragma("unroll") for (int m = 0; m < 4; ++m) _Pragma("unroll") for (int k = 0; k < 2; ++k) dst[m][k] = *(const LAS bf16x8*)(lds + PG8_SA(b, h) + aoff + m * 2048 + k * 1024); } while (0)
; #define PG8_LDB(dst, b, h) do { _Pragma("unroll") for (int n = 0; n < 2; ++n) _Pragma("unroll") for (int k = 0; k < 2; ++k) dst[n][k] = *(const LAS bf16x8*)(lds + PG8_SB(b, h) + boff + n * 2048 + k * 1024); } while (0)
; #define PG8_MMA(ai, bj, At, Bt) do { __builtin_amdgcn_s_setprio(1); _Pragma("unroll") for (int m = 0; m < 4; ++m) _Pragma("unroll") for (int n = 0; n < 2; ++n) _Pragma("unroll") for (int k = 0; k < 2; ++k) \
;         acc[ai][bj][m][n] = __builtin_amdgcn_mfma_f32_16x16x32_bf16(Bt[n][k], At[m][k], acc[ai][bj][m][n], 0, 0, 0); __builtin_amdgcn_s_setprio(0); } while (0)
; #define PG8_WAIT_V(n) asm volatile("s_waitcnt vmcnt(" #n ")" ::: "memory")
; #define PG8_WAIT_L(n) asm volatile("s_waitcnt lgkmcnt(" #n ")" ::: "memory")
; #define PG8_BAR __builtin_amdgcn_s_barrier()
; #define PG8_SCHED __builtin_amdgcn_sched_barrier(0)
; template <class Epi, bool ALIGN_EPI, int K, int LDA, int LDB>
; __device__ __forceinline__ void gemm_phase(LAS unsigned char* lds, const int wid, const Gemm g, const StaticOrder& S, const Epi& E) {
;     ...
;             const bool last = (t == nt - 2);
;             const char* a1 = cA + (size_t)(t + 1) * kstep;
;             const char* a2 = last ? nA : cA + (size_t)(t + 2) * kstep; const char* b2 = last ? nB : cB + (size_t)(t + 2) * kstep;
;             const char* a3 = a2 + kstep; const char* b3 = b2 + kstep;
;             PG8_LDB(B0, 0, 0); PG8_LDB(B1, 0, 1); PG8_SCHED; PG8_LDA(At, 0, 0); PG8_STAGE(PG8_SA(1, 1), a1 + hA, voffA);
;             PG8_WAIT_V(8); PG8_WAIT_L(0); PG8_BAR; PG8_MMA(0, 0, At, B0); PG8_MMA(0, 1, At, B1); PG8_BAR; PG8_SCHED;
;             PG8_LDA(At, 0, 1); PG8_STAGE(PG8_SB(0, 0), b2, voffB); PG8_STAGE(PG8_SB(0, 1), b2 + hB, voffB); PG8_STAGE(PG8_SA(0, 0), a2, voffA);
;             PG8_WAIT_V(8); PG8_WAIT_L(0); PG8_BAR; PG8_MMA(1, 0, At, B0); PG8_MMA(1, 1, At, B1); PG8_BAR; PG8_SCHED;
.LBB0_1137:
	ds_read_b128 v[128:131], v175
	ds_read_b128 v[132:135], v175 offset:1024
	ds_read_b128 v[136:139], v175 offset:2048
	ds_read_b128 v[140:143], v175 offset:3072
	ds_read_b128 v[144:147], v176
	ds_read_b128 v[164:167], v176 offset:1024
	ds_read_b128 v[168:171], v176 offset:2048
	ds_read_b128 v[178:181], v176 offset:3072
	s_add_u32 s28, s26, 0x100
	s_addc_u32 s29, s27, 0
	s_cmp_eq_u32 s67, 40
	s_cselect_b32 s35, s7, s29
	s_cselect_b32 s34, s6, s28
	s_cselect_b32 s31, s25, s66
	s_cselect_b32 s30, s24, s65
	s_add_i32 m0, s36, 0xc000
	ds_read_b128 v[182:185], v177
	ds_read_b128 v[186:189], v177 offset:1024
	ds_read_b128 v[190:193], v177 offset:2048
	ds_read_b128 v[194:197], v177 offset:3072
	ds_read_b128 v[198:201], v177 offset:4096
	ds_read_b128 v[202:205], v177 offset:5120
	ds_read_b128 v[206:209], v177 offset:6144
	ds_read_b128 v[210:213], v177 offset:7168
	global_load_lds_dwordx4 v156, s[26:27]
	s_add_i32 m0, s36, 0xe000
	s_nop 0
	global_load_lds_dwordx4 v158, s[26:27]
	s_waitcnt vmcnt(8)
	s_waitcnt lgkmcnt(0)
	s_barrier
	s_setprio 1
	s_waitcnt lgkmcnt(0)
	v_mfma_f32_16x16x32_bf16 v[124:127], v[128:131], v[182:185], v[124:127]
	v_mfma_f32_16x16x32_bf16 v[116:119], v[136:139], v[182:185], v[116:119]
	v_mfma_f32_16x16x32_bf16 v[120:123], v[128:131], v[190:193], v[120:123]
	v_mfma_f32_16x16x32_bf16 v[112:115], v[136:139], v[190:193], v[112:115]
	v_mfma_f32_16x16x32_bf16 v[92:95], v[128:131], v[198:201], v[92:95]
	v_mfma_f32_16x16x32_bf16 v[88:91], v[136:139], v[198:201], v[88:91]
	v_mfma_f32_16x16x32_bf16 v[76:79], v[128:131], v[206:209], v[76:79]
	v_mfma_f32_16x16x32_bf16 v[72:75], v[136:139], v[206:209], v[72:75]
	v_mfma_f32_16x16x32_bf16 v[124:127], v[132:135], v[186:189], v[124:127]
	v_mfma_f32_16x16x32_bf16 v[116:119], v[140:143], v[186:189], v[116:119]
	v_mfma_f32_16x16x32_bf16 v[120:123], v[132:135], v[194:197], v[120:123]
	v_mfma_f32_16x16x32_bf16 v[112:115], v[140:143], v[194:197], v[112:115]
	v_mfma_f32_16x16x32_bf16 v[92:95], v[132:135], v[202:205], v[92:95]
	v_mfma_f32_16x16x32_bf16 v[88:91], v[140:143], v[202:205], v[88:91]
	v_mfma_f32_16x16x32_bf16 v[76:79], v[132:135], v[210:213], v[76:79]
	v_mfma_f32_16x16x32_bf16 v[72:75], v[140:143], v[210:213], v[72:75]
	s_setprio 0
	s_setprio 1
	v_mfma_f32_16x16x32_bf16 v[108:111], v[144:147], v[182:185], v[108:111]
	v_mfma_f32_16x16x32_bf16 v[104:107], v[168:171], v[182:185], v[104:107]
	v_mfma_f32_16x16x32_bf16 v[100:103], v[144:147], v[190:193], v[100:103]
	v_mfma_f32_16x16x32_bf16 v[96:99], v[168:171], v[190:193], v[96:99]
	v_mfma_f32_16x16x32_bf16 v[84:87], v[144:147], v[198:201], v[84:87]
	v_mfma_f32_16x16x32_bf16 v[80:83], v[168:171], v[198:201], v[80:83]
	v_mfma_f32_16x16x32_bf16 v[68:71], v[144:147], v[206:209], v[68:71]
	v_mfma_f32_16x16x32_bf16 v[64:67], v[168:171], v[206:209], v[64:67]
	v_mfma_f32_16x16x32_bf16 v[108:111], v[164:167], v[186:189], v[108:111]
	v_mfma_f32_16x16x32_bf16 v[104:107], v[178:181], v[186:189], v[104:107]
	v_mfma_f32_16x16x32_bf16 v[100:103], v[164:167], v[194:197], v[100:103]
	v_mfma_f32_16x16x32_bf16 v[96:99], v[178:181], v[194:197], v[96:99]
	v_mfma_f32_16x16x32_bf16 v[84:87], v[164:167], v[202:205], v[84:87]
	v_mfma_f32_16x16x32_bf16 v[80:83], v[178:181], v[202:205], v[80:83]
	v_mfma_f32_16x16x32_bf16 v[68:71], v[164:167], v[210:213], v[68:71]
	v_mfma_f32_16x16x32_bf16 v[64:67], v[178:181], v[210:213], v[64:67]
	s_setprio 0
	s_barrier
	s_add_u32 s98, s30, s12
	s_addc_u32 s99, s31, s13
	s_add_u32 s100, s34, s12
	s_addc_u32 s101, s35, s13
	s_add_i32 s26, s54, s33
	s_mov_b32 m0, s26
	ds_read_b128 v[182:185], v177 offset:16384
	ds_read_b128 v[186:189], v177 offset:17408
	ds_read_b128 v[190:193], v177 offset:18432
	ds_read_b128 v[194:197], v177 offset:19456
	ds_read_b128 v[198:201], v177 offset:20480
	ds_read_b128 v[202:205], v177 offset:21504
	ds_read_b128 v[206:209], v177 offset:22528
	ds_read_b128 v[210:213], v177 offset:23552
	global_load_lds_dwordx4 v150, s[30:31]
	s_add_i32 m0, s26, 0x2000
	s_add_u32 s26, s30, 0xb0000
	s_addc_u32 s27, s31, 0
	s_add_i32 s52, s55, s33
	global_load_lds_dwordx4 v154, s[30:31]
	s_mov_b32 m0, s52
	s_nop 0
	global_load_lds_dwordx4 v150, s[26:27]
	s_add_i32 m0, s52, 0x2000
	s_nop 0
	global_load_lds_dwordx4 v154, s[26:27]
	s_mov_b32 m0, s36
	s_nop 0
	global_load_lds_dwordx4 v148, s[34:35]
	s_mov_b32 m0, s37
	s_nop 0
	global_load_lds_dwordx4 v152, s[34:35]
	s_waitcnt vmcnt(8)
	s_waitcnt lgkmcnt(0)
	s_barrier
	s_setprio 1
	s_waitcnt lgkmcnt(0)
	v_mfma_f32_16x16x32_bf16 v[60:63], v[128:131], v[182:185], v[60:63]
	v_mfma_f32_16x16x32_bf16 v[56:59], v[136:139], v[182:185], v[56:59]
	v_mfma_f32_16x16x32_bf16 v[44:47], v[128:131], v[190:193], v[44:47]
	v_mfma_f32_16x16x32_bf16 v[40:43], v[136:139], v[190:193], v[40:43]
	v_mfma_f32_16x16x32_bf16 v[36:39], v[128:131], v[198:201], v[36:39]
	v_mfma_f32_16x16x32_bf16 v[32:35], v[136:139], v[198:201], v[32:35]
	v_mfma_f32_16x16x32_bf16 v[20:23], v[128:131], v[206:209], v[20:23]
	v_mfma_f32_16x16x32_bf16 v[16:19], v[136:139], v[206:209], v[16:19]
	v_mfma_f32_16x16x32_bf16 v[60:63], v[132:135], v[186:189], v[60:63]
	v_mfma_f32_16x16x32_bf16 v[56:59], v[140:143], v[186:189], v[56:59]
	v_mfma_f32_16x16x32_bf16 v[44:47], v[132:135], v[194:197], v[44:47]
	v_mfma_f32_16x16x32_bf16 v[40:43], v[140:143], v[194:197], v[40:43]
	v_mfma_f32_16x16x32_bf16 v[36:39], v[132:135], v[202:205], v[36:39]
	v_mfma_f32_16x16x32_bf16 v[32:35], v[140:143], v[202:205], v[32:35]
	v_mfma_f32_16x16x32_bf16 v[20:23], v[132:135], v[210:213], v[20:23]
	v_mfma_f32_16x16x32_bf16 v[16:19], v[140:143], v[210:213], v[16:19]
	s_setprio 0
	s_setprio 1
	v_mfma_f32_16x16x32_bf16 v[52:55], v[144:147], v[182:185], v[52:55]
	v_mfma_f32_16x16x32_bf16 v[48:51], v[168:171], v[182:185], v[48:51]
	v_mfma_f32_16x16x32_bf16 v[28:31], v[144:147], v[190:193], v[28:31]
	v_mfma_f32_16x16x32_bf16 v[24:27], v[168:171], v[190:193], v[24:27]
	v_mfma_f32_16x16x32_bf16 v[12:15], v[144:147], v[198:201], v[12:15]
	v_mfma_f32_16x16x32_bf16 v[8:11], v[168:171], v[198:201], v[8:11]
	v_mfma_f32_16x16x32_bf16 v[4:7], v[144:147], v[206:209], v[4:7]
	v_mfma_f32_16x16x32_bf16 v[0:3], v[168:171], v[206:209], v[0:3]
	v_mfma_f32_16x16x32_bf16 v[52:55], v[164:167], v[186:189], v[52:55]
	v_mfma_f32_16x16x32_bf16 v[48:51], v[178:181], v[186:189], v[48:51]
	v_mfma_f32_16x16x32_bf16 v[28:31], v[164:167], v[194:197], v[28:31]
	v_mfma_f32_16x16x32_bf16 v[24:27], v[178:181], v[194:197], v[24:27]
	v_mfma_f32_16x16x32_bf16 v[12:15], v[164:167], v[202:205], v[12:15]
	v_mfma_f32_16x16x32_bf16 v[8:11], v[178:181], v[202:205], v[8:11]
	v_mfma_f32_16x16x32_bf16 v[4:7], v[164:167], v[210:213], v[4:7]
	v_mfma_f32_16x16x32_bf16 v[0:3], v[178:181], v[210:213], v[0:3]
	s_setprio 0
	s_barrier
; #define PG8_STAGE(bufoff, gbase, voff) do { _Pragma("unroll") for (int _i = 0; _i < 2; ++_i) \
;         __builtin_amdgcn_global_load_lds((const unsigned*)((const char*)(gbase) + (voff)[_i]), (LAS unsigned*)(lds + (bufoff) + ldsw + _i * 8192), 16, 0, 0); } while (0)
; #define PG8_LDA(dst, b, h) do { _Pragma("unroll") for (int m = 0; m < 4; ++m) _Pragma("unroll") for (int k = 0; k < 2; ++k) dst[m][k] = *(const LAS bf16x8*)(lds + PG8_SA(b, h) + aoff + m * 2048 + k * 1024); } while (0)
; #define PG8_LDB(dst, b, h) do { _Pragma("unroll") for (int n = 0; n < 2; ++n) _Pragma("unroll") for (int k = 0; k < 2; ++k) dst[n][k] = *(const LAS bf16x8*)(lds + PG8_SB(b, h) + boff + n * 2048 + k * 1024); } while (0)
; #define PG8_MMA(ai, bj, At, Bt) do { __builtin_amdgcn_s_setprio(1); _Pragma("unroll") for (int m = 0; m < 4; ++m) _Pragma("unroll") for (int n = 0; n < 2; ++n) _Pragma("unroll") for (int k = 0; k < 2; ++k) \
;         acc[ai][bj][m][n] = __builtin_amdgcn_mfma_f32_16x16x32_bf16(Bt[n][k], At[m][k], acc[ai][bj][m][n], 0, 0, 0); __builtin_amdgcn_s_setprio(0); } while (0)
; #define PG8_WAIT_V(n) asm volatile("s_waitcnt vmcnt(" #n ")" ::: "memory")
; #define PG8_WAIT_L(n) asm volatile("s_waitcnt lgkmcnt(" #n ")" ::: "memory")
; #define PG8_BAR __builtin_amdgcn_s_barrier()
; #define PG8_SCHED __builtin_amdgcn_sched_barrier(0)
; template <class Epi, bool ALIGN_EPI, int K, int LDA, int LDB>
; __device__ __forceinline__ void gemm_phase(LAS unsigned char* lds, const int wid, const Gemm g, const StaticOrder& S, const Epi& E) {
;     ...
;             PG8_LDB(B0, 1, 0); PG8_LDB(B1, 1, 1); PG8_SCHED; PG8_LDA(At, 1, 0); PG8_STAGE(PG8_SA(0, 1), a2 + hA, voffA);
;             PG8_WAIT_V(8); PG8_WAIT_L(0); PG8_BAR; PG8_MMA(0, 0, At, B0); PG8_MMA(0, 1, At, B1); PG8_BAR; PG8_SCHED;
;             PG8_LDA(At, 1, 1); PG8_STAGE(PG8_SB(1, 0), b3, voffB); PG8_STAGE(PG8_SB(1, 1), b3 + hB, voffB); PG8_STAGE(PG8_SA(1, 0), a3, voffA);
;             PG8_WAIT_V(8); PG8_WAIT_L(0); PG8_BAR; PG8_MMA(1, 0, At, B0); PG8_MMA(1, 1, At, B1); PG8_BAR; PG8_SCHED;
;         }
;         if constexpr (ALIGN_EPI) { if (wr == 0) PG8_BAR; }
	s_add_i32 s52, 0, 0x18000
	s_add_i32 s53, 0, 0x1c000
	v_add_u32_e32 v140, s52, v174
	v_add_u32_e32 v178, s53, v174
	ds_read_b128 v[128:131], v140
	ds_read_b128 v[132:135], v140 offset:1024
	ds_read_b128 v[136:139], v140 offset:2048
	ds_read_b128 v[140:143], v140 offset:3072
	ds_read_b128 v[144:147], v178
	ds_read_b128 v[164:167], v178 offset:1024
	ds_read_b128 v[168:171], v178 offset:2048
	ds_read_b128 v[178:181], v178 offset:3072
	s_add_u32 s26, s34, 0xb0000
	s_addc_u32 s27, s35, 0
	s_mov_b32 m0, s38
	ds_read_b128 v[182:185], v177 offset:32768
	ds_read_b128 v[186:189], v177 offset:33792
	ds_read_b128 v[190:193], v177 offset:34816
	ds_read_b128 v[194:197], v177 offset:35840
	ds_read_b128 v[198:201], v177 offset:36864
	ds_read_b128 v[202:205], v177 offset:37888
	ds_read_b128 v[206:209], v177 offset:38912
	ds_read_b128 v[210:213], v177 offset:39936
	global_load_lds_dwordx4 v148, s[26:27]
	s_mov_b32 m0, s39
	s_nop 0
	global_load_lds_dwordx4 v152, s[26:27]
	s_waitcnt vmcnt(8)
	s_waitcnt lgkmcnt(0)
	s_barrier
	s_setprio 1
	s_waitcnt lgkmcnt(0)
	v_mfma_f32_16x16x32_bf16 v[124:127], v[128:131], v[182:185], v[124:127]
	v_mfma_f32_16x16x32_bf16 v[116:119], v[136:139], v[182:185], v[116:119]
	v_mfma_f32_16x16x32_bf16 v[120:123], v[128:131], v[190:193], v[120:123]
	v_mfma_f32_16x16x32_bf16 v[112:115], v[136:139], v[190:193], v[112:115]
	v_mfma_f32_16x16x32_bf16 v[92:95], v[128:131], v[198:201], v[92:95]
	v_mfma_f32_16x16x32_bf16 v[88:91], v[136:139], v[198:201], v[88:91]
	v_mfma_f32_16x16x32_bf16 v[76:79], v[128:131], v[206:209], v[76:79]
	v_mfma_f32_16x16x32_bf16 v[72:75], v[136:139], v[206:209], v[72:75]
	v_mfma_f32_16x16x32_bf16 v[124:127], v[132:135], v[186:189], v[124:127]
	v_mfma_f32_16x16x32_bf16 v[116:119], v[140:143], v[186:189], v[116:119]
	v_mfma_f32_16x16x32_bf16 v[120:123], v[132:135], v[194:197], v[120:123]
	v_mfma_f32_16x16x32_bf16 v[112:115], v[140:143], v[194:197], v[112:115]
	v_mfma_f32_16x16x32_bf16 v[92:95], v[132:135], v[202:205], v[92:95]
	v_mfma_f32_16x16x32_bf16 v[88:91], v[140:143], v[202:205], v[88:91]
	v_mfma_f32_16x16x32_bf16 v[76:79], v[132:135], v[210:213], v[76:79]
	v_mfma_f32_16x16x32_bf16 v[72:75], v[140:143], v[210:213], v[72:75]
	s_setprio 0
	s_setprio 1
	v_mfma_f32_16x16x32_bf16 v[108:111], v[144:147], v[182:185], v[108:111]
	v_mfma_f32_16x16x32_bf16 v[104:107], v[168:171], v[182:185], v[104:107]
	v_mfma_f32_16x16x32_bf16 v[100:103], v[144:147], v[190:193], v[100:103]
	v_mfma_f32_16x16x32_bf16 v[96:99], v[168:171], v[190:193], v[96:99]
	v_mfma_f32_16x16x32_bf16 v[84:87], v[144:147], v[198:201], v[84:87]
	v_mfma_f32_16x16x32_bf16 v[80:83], v[168:171], v[198:201], v[80:83]
	v_mfma_f32_16x16x32_bf16 v[68:71], v[144:147], v[206:209], v[68:71]
	v_mfma_f32_16x16x32_bf16 v[64:67], v[168:171], v[206:209], v[64:67]
	v_mfma_f32_16x16x32_bf16 v[108:111], v[164:167], v[186:189], v[108:111]
	v_mfma_f32_16x16x32_bf16 v[104:107], v[178:181], v[186:189], v[104:107]
	v_mfma_f32_16x16x32_bf16 v[100:103], v[164:167], v[194:197], v[100:103]
	v_mfma_f32_16x16x32_bf16 v[96:99], v[178:181], v[194:197], v[96:99]
	v_mfma_f32_16x16x32_bf16 v[84:87], v[164:167], v[202:205], v[84:87]
	v_mfma_f32_16x16x32_bf16 v[80:83], v[178:181], v[202:205], v[80:83]
	v_mfma_f32_16x16x32_bf16 v[68:71], v[164:167], v[210:213], v[68:71]
	v_mfma_f32_16x16x32_bf16 v[64:67], v[178:181], v[210:213], v[64:67]
	s_setprio 0
	s_barrier
	s_add_i32 s26, s52, s33
	s_mov_b32 m0, s26
	ds_read_b128 v[182:185], v177 offset:49152
	ds_read_b128 v[186:189], v177 offset:50176
	ds_read_b128 v[190:193], v177 offset:51200
	ds_read_b128 v[194:197], v177 offset:52224
	ds_read_b128 v[198:201], v177 offset:53248
	ds_read_b128 v[202:205], v177 offset:54272
	ds_read_b128 v[206:209], v177 offset:55296
	ds_read_b128 v[210:213], v177 offset:56320
	global_load_lds_dwordx4 v150, s[98:99]
	s_add_i32 m0, s26, 0x2000
	s_add_u32 s26, s30, 0xb0080
	s_addc_u32 s27, s31, 0
	s_add_i32 s30, s53, s33
	global_load_lds_dwordx4 v154, s[98:99]
	s_mov_b32 m0, s30
	s_nop 0
	global_load_lds_dwordx4 v150, s[26:27]
	s_add_i32 m0, s30, 0x2000
	s_nop 0
	global_load_lds_dwordx4 v154, s[26:27]
	s_mov_b32 m0, s48
	s_nop 0
	global_load_lds_dwordx4 v148, s[100:101]
	s_mov_b32 m0, s49
	s_nop 0
	global_load_lds_dwordx4 v152, s[100:101]
	s_waitcnt vmcnt(8)
	s_waitcnt lgkmcnt(0)
	s_barrier
	s_setprio 1
	s_waitcnt lgkmcnt(0)
	v_mfma_f32_16x16x32_bf16 v[60:63], v[128:131], v[182:185], v[60:63]
	v_mfma_f32_16x16x32_bf16 v[56:59], v[136:139], v[182:185], v[56:59]
	v_mfma_f32_16x16x32_bf16 v[44:47], v[128:131], v[190:193], v[44:47]
	v_mfma_f32_16x16x32_bf16 v[40:43], v[136:139], v[190:193], v[40:43]
	v_mfma_f32_16x16x32_bf16 v[36:39], v[128:131], v[198:201], v[36:39]
	v_mfma_f32_16x16x32_bf16 v[32:35], v[136:139], v[198:201], v[32:35]
	v_mfma_f32_16x16x32_bf16 v[20:23], v[128:131], v[206:209], v[20:23]
	v_mfma_f32_16x16x32_bf16 v[16:19], v[136:139], v[206:209], v[16:19]
	v_mfma_f32_16x16x32_bf16 v[60:63], v[132:135], v[186:189], v[60:63]
	v_mfma_f32_16x16x32_bf16 v[56:59], v[140:143], v[186:189], v[56:59]
	v_mfma_f32_16x16x32_bf16 v[44:47], v[132:135], v[194:197], v[44:47]
	v_mfma_f32_16x16x32_bf16 v[40:43], v[140:143], v[194:197], v[40:43]
	v_mfma_f32_16x16x32_bf16 v[36:39], v[132:135], v[202:205], v[36:39]
	v_mfma_f32_16x16x32_bf16 v[32:35], v[140:143], v[202:205], v[32:35]
	v_mfma_f32_16x16x32_bf16 v[20:23], v[132:135], v[210:213], v[20:23]
	v_mfma_f32_16x16x32_bf16 v[16:19], v[140:143], v[210:213], v[16:19]
	s_setprio 0
	s_setprio 1
	v_mfma_f32_16x16x32_bf16 v[52:55], v[144:147], v[182:185], v[52:55]
	v_mfma_f32_16x16x32_bf16 v[48:51], v[168:171], v[182:185], v[48:51]
	v_mfma_f32_16x16x32_bf16 v[28:31], v[144:147], v[190:193], v[28:31]
	v_mfma_f32_16x16x32_bf16 v[24:27], v[168:171], v[190:193], v[24:27]
	v_mfma_f32_16x16x32_bf16 v[12:15], v[144:147], v[198:201], v[12:15]
	v_mfma_f32_16x16x32_bf16 v[8:11], v[168:171], v[198:201], v[8:11]
	v_mfma_f32_16x16x32_bf16 v[4:7], v[144:147], v[206:209], v[4:7]
	v_mfma_f32_16x16x32_bf16 v[0:3], v[168:171], v[206:209], v[0:3]
	v_mfma_f32_16x16x32_bf16 v[52:55], v[164:167], v[186:189], v[52:55]
	v_mfma_f32_16x16x32_bf16 v[48:51], v[178:181], v[186:189], v[48:51]
	v_mfma_f32_16x16x32_bf16 v[28:31], v[164:167], v[194:197], v[28:31]
	v_mfma_f32_16x16x32_bf16 v[24:27], v[178:181], v[194:197], v[24:27]
	v_mfma_f32_16x16x32_bf16 v[12:15], v[164:167], v[202:205], v[12:15]
	v_mfma_f32_16x16x32_bf16 v[8:11], v[178:181], v[202:205], v[8:11]
	v_mfma_f32_16x16x32_bf16 v[4:7], v[164:167], v[210:213], v[4:7]
	v_mfma_f32_16x16x32_bf16 v[0:3], v[178:181], v[210:213], v[0:3]
	s_setprio 0
	s_barrier
	s_add_i32 s67, s67, 2
	s_add_u32 s65, s65, 0x100
	s_addc_u32 s66, s66, 0
	s_cmp_gt_u32 s67, 41
	s_mov_b64 s[26:27], s[28:29]
	s_cbranch_scc0 .LBB0_1137
	s_and_b64 vcc, exec, s[14:15]
	s_cbranch_vccz .LBB0_1140
	s_barrier

; #define PG8_STAGE(bufoff, gbase, voff) do { _Pragma("unroll") for (int _i = 0; _i < 2; ++_i) \
;         __builtin_amdgcn_global_load_lds((const unsigned*)((const char*)(gbase) + (voff)[_i]), (LAS unsigned*)(lds + (bufoff) + ldsw + _i * 8192), 16, 0, 0); } while (0)
; #define PG8_LDA(dst, b, h) do { _Pragma("unroll") for (int m = 0; m < 4; ++m) _Pragma("unroll") for (int k = 0; k < 2; ++k) dst[m][k] = *(const LAS bf16x8*)(lds + PG8_SA(b, h) + aoff + m * 2048 + k * 1024); } while (0)
; #define PG8_LDB(dst, b, h) do { _Pragma("unroll") for (int n = 0; n < 2; ++n) _Pragma("unroll") for (int k = 0; k < 2; ++k) dst[n][k] = *(const LAS bf16x8*)(lds + PG8_SB(b, h) + boff + n * 2048 + k * 1024); } while (0)
; #define PG8_MMA(ai, bj, At, Bt) do { __builtin_amdgcn_s_setprio(1); _Pragma("unroll") for (int m = 0; m < 4; ++m) _Pragma("unroll") for (int n = 0; n < 2; ++n) _Pragma("unroll") for (int k = 0; k < 2; ++k) \
;         acc[ai][bj][m][n] = __builtin_amdgcn_mfma_f32_16x16x32_bf16(Bt[n][k], At[m][k], acc[ai][bj][m][n], 0, 0, 0); __builtin_amdgcn_s_setprio(0); } while (0)
; #define PG8_WAIT_V(n) asm volatile("s_waitcnt vmcnt(" #n ")" ::: "memory")
; #define PG8_WAIT_L(n) asm volatile("s_waitcnt lgkmcnt(" #n ")" ::: "memory")
; #define PG8_BAR __builtin_amdgcn_s_barrier()
; #define PG8_SCHED __builtin_amdgcn_sched_barrier(0)
; template <class Epi, bool ALIGN_EPI, int K, int LDA, int LDB>
; __device__ __forceinline__ void gemm_phase(LAS unsigned char* lds, const int wid, const Gemm g, const StaticOrder& S, const Epi& E) {
;     ...
;             const bool last = (t == nt - 2);
;             const char* a1 = cA + (size_t)(t + 1) * kstep;
;             const char* a2 = last ? nA : cA + (size_t)(t + 2) * kstep; const char* b2 = last ? nB : cB + (size_t)(t + 2) * kstep;
;             const char* a3 = a2 + kstep; const char* b3 = b2 + kstep;
;             PG8_LDB(B0, 0, 0); PG8_LDB(B1, 0, 1); PG8_SCHED; PG8_LDA(At, 0, 0); PG8_STAGE(PG8_SA(1, 1), a1 + hA, voffA);
;             PG8_WAIT_V(8); PG8_WAIT_L(0); PG8_BAR; PG8_MMA(0, 0, At, B0); PG8_MMA(0, 1, At, B1); PG8_BAR; PG8_SCHED;
;             PG8_LDA(At, 0, 1); PG8_STAGE(PG8_SB(0, 0), b2, voffB); PG8_STAGE(PG8_SB(0, 1), b2 + hB, voffB); PG8_STAGE(PG8_SA(0, 0), a2, voffA);
;             PG8_WAIT_V(8); PG8_WAIT_L(0); PG8_BAR; PG8_MMA(1, 0, At, B0); PG8_MMA(1, 1, At, B1); PG8_BAR; PG8_SCHED;
.LBB0_1279:
	ds_read_b128 v[144:147], v151
	ds_read_b128 v[154:157], v151 offset:1024
	ds_read_b128 v[158:161], v151 offset:2048
	ds_read_b128 v[162:165], v151 offset:3072
	ds_read_b128 v[166:169], v152
	ds_read_b128 v[170:173], v152 offset:1024
	ds_read_b128 v[174:177], v152 offset:2048
	ds_read_b128 v[178:181], v152 offset:3072
	s_add_u32 s36, s34, 0xfffc0080
	s_addc_u32 s37, s35, -1
	s_cmp_eq_u32 s61, 12
	s_cselect_b32 s39, s7, s37
	s_cselect_b32 s38, s25, s36
	s_cselect_b32 s37, s23, s60
	s_cselect_b32 s36, s42, s59
	s_add_i32 m0, s31, 0xc000
	ds_read_b128 v[182:185], v153
	ds_read_b128 v[186:189], v153 offset:1024
	ds_read_b128 v[190:193], v153 offset:2048
	ds_read_b128 v[194:197], v153 offset:3072
	ds_read_b128 v[198:201], v153 offset:4096
	ds_read_b128 v[202:205], v153 offset:5120
	ds_read_b128 v[206:209], v153 offset:6144
	ds_read_b128 v[210:213], v153 offset:7168
	global_load_lds_dwordx4 v136, s[34:35]
	s_add_i32 m0, s31, 0xe000
	s_nop 0
	global_load_lds_dwordx4 v138, s[34:35]
	s_waitcnt vmcnt(8)
	s_waitcnt lgkmcnt(0)
	s_barrier
	s_setprio 1
	s_waitcnt lgkmcnt(0)
	v_mfma_f32_16x16x32_bf16 v[124:127], v[144:147], v[182:185], v[124:127]
	v_mfma_f32_16x16x32_bf16 v[120:123], v[158:161], v[182:185], v[120:123]
	v_mfma_f32_16x16x32_bf16 v[108:111], v[144:147], v[190:193], v[108:111]
	v_mfma_f32_16x16x32_bf16 v[104:107], v[158:161], v[190:193], v[104:107]
	v_mfma_f32_16x16x32_bf16 v[92:95], v[144:147], v[198:201], v[92:95]
	v_mfma_f32_16x16x32_bf16 v[88:91], v[158:161], v[198:201], v[88:91]
	v_mfma_f32_16x16x32_bf16 v[76:79], v[144:147], v[206:209], v[76:79]
	v_mfma_f32_16x16x32_bf16 v[72:75], v[158:161], v[206:209], v[72:75]
	v_mfma_f32_16x16x32_bf16 v[124:127], v[154:157], v[186:189], v[124:127]
	v_mfma_f32_16x16x32_bf16 v[120:123], v[162:165], v[186:189], v[120:123]
	v_mfma_f32_16x16x32_bf16 v[108:111], v[154:157], v[194:197], v[108:111]
	v_mfma_f32_16x16x32_bf16 v[104:107], v[162:165], v[194:197], v[104:107]
	v_mfma_f32_16x16x32_bf16 v[92:95], v[154:157], v[202:205], v[92:95]
	v_mfma_f32_16x16x32_bf16 v[88:91], v[162:165], v[202:205], v[88:91]
	v_mfma_f32_16x16x32_bf16 v[76:79], v[154:157], v[210:213], v[76:79]
	v_mfma_f32_16x16x32_bf16 v[72:75], v[162:165], v[210:213], v[72:75]
	s_setprio 0
	s_setprio 1
	v_mfma_f32_16x16x32_bf16 v[116:119], v[166:169], v[182:185], v[116:119]
	v_mfma_f32_16x16x32_bf16 v[112:115], v[174:177], v[182:185], v[112:115]
	v_mfma_f32_16x16x32_bf16 v[100:103], v[166:169], v[190:193], v[100:103]
	v_mfma_f32_16x16x32_bf16 v[96:99], v[174:177], v[190:193], v[96:99]
	v_mfma_f32_16x16x32_bf16 v[84:87], v[166:169], v[198:201], v[84:87]
	v_mfma_f32_16x16x32_bf16 v[80:83], v[174:177], v[198:201], v[80:83]
	v_mfma_f32_16x16x32_bf16 v[68:71], v[166:169], v[206:209], v[68:71]
	v_mfma_f32_16x16x32_bf16 v[64:67], v[174:177], v[206:209], v[64:67]
	v_mfma_f32_16x16x32_bf16 v[116:119], v[170:173], v[186:189], v[116:119]
	v_mfma_f32_16x16x32_bf16 v[112:115], v[178:181], v[186:189], v[112:115]
	v_mfma_f32_16x16x32_bf16 v[100:103], v[170:173], v[194:197], v[100:103]
	v_mfma_f32_16x16x32_bf16 v[96:99], v[178:181], v[194:197], v[96:99]
	v_mfma_f32_16x16x32_bf16 v[84:87], v[170:173], v[202:205], v[84:87]
	v_mfma_f32_16x16x32_bf16 v[80:83], v[178:181], v[202:205], v[80:83]
	v_mfma_f32_16x16x32_bf16 v[68:71], v[170:173], v[210:213], v[68:71]
	v_mfma_f32_16x16x32_bf16 v[64:67], v[178:181], v[210:213], v[64:67]
	s_setprio 0
	s_barrier
	s_add_u32 s98, s36, s12
	s_addc_u32 s99, s37, s13
	s_add_u32 s100, s38, s12
	s_addc_u32 s101, s39, s13
	s_add_i32 s52, s57, s3
	s_mov_b32 m0, s52
	ds_read_b128 v[182:185], v153 offset:16384
	ds_read_b128 v[186:189], v153 offset:17408
	ds_read_b128 v[190:193], v153 offset:18432
	ds_read_b128 v[194:197], v153 offset:19456
	ds_read_b128 v[198:201], v153 offset:20480
	ds_read_b128 v[202:205], v153 offset:21504
	ds_read_b128 v[206:209], v153 offset:22528
	ds_read_b128 v[210:213], v153 offset:23552
	global_load_lds_dwordx4 v130, s[36:37]
	s_add_i32 m0, s52, 0x2000
	s_add_u32 s62, s36, 0x40000
	s_addc_u32 s63, s37, 0
	s_add_i32 s52, s58, s3
	global_load_lds_dwordx4 v134, s[36:37]
	s_mov_b32 m0, s52
	s_nop 0
	global_load_lds_dwordx4 v130, s[62:63]
	s_add_i32 m0, s52, 0x2000
	s_nop 0
	global_load_lds_dwordx4 v134, s[62:63]
	s_mov_b32 m0, s31
	s_nop 0
	global_load_lds_dwordx4 v128, s[38:39]
	s_mov_b32 m0, s33
	s_nop 0
	global_load_lds_dwordx4 v132, s[38:39]
	s_waitcnt vmcnt(8)
	s_waitcnt lgkmcnt(0)
	s_barrier
	s_setprio 1
	s_waitcnt lgkmcnt(0)
	v_mfma_f32_16x16x32_bf16 v[60:63], v[144:147], v[182:185], v[60:63]
	v_mfma_f32_16x16x32_bf16 v[56:59], v[158:161], v[182:185], v[56:59]
	v_mfma_f32_16x16x32_bf16 v[44:47], v[144:147], v[190:193], v[44:47]
	v_mfma_f32_16x16x32_bf16 v[40:43], v[158:161], v[190:193], v[40:43]
	v_mfma_f32_16x16x32_bf16 v[28:31], v[144:147], v[198:201], v[28:31]
	v_mfma_f32_16x16x32_bf16 v[24:27], v[158:161], v[198:201], v[24:27]
	v_mfma_f32_16x16x32_bf16 v[12:15], v[144:147], v[206:209], v[12:15]
	v_mfma_f32_16x16x32_bf16 v[8:11], v[158:161], v[206:209], v[8:11]
	v_mfma_f32_16x16x32_bf16 v[60:63], v[154:157], v[186:189], v[60:63]
	v_mfma_f32_16x16x32_bf16 v[56:59], v[162:165], v[186:189], v[56:59]
	v_mfma_f32_16x16x32_bf16 v[44:47], v[154:157], v[194:197], v[44:47]
	v_mfma_f32_16x16x32_bf16 v[40:43], v[162:165], v[194:197], v[40:43]
	v_mfma_f32_16x16x32_bf16 v[28:31], v[154:157], v[202:205], v[28:31]
	v_mfma_f32_16x16x32_bf16 v[24:27], v[162:165], v[202:205], v[24:27]
	v_mfma_f32_16x16x32_bf16 v[12:15], v[154:157], v[210:213], v[12:15]
	v_mfma_f32_16x16x32_bf16 v[8:11], v[162:165], v[210:213], v[8:11]
	s_setprio 0
	s_setprio 1
	v_mfma_f32_16x16x32_bf16 v[52:55], v[166:169], v[182:185], v[52:55]
	v_mfma_f32_16x16x32_bf16 v[48:51], v[174:177], v[182:185], v[48:51]
	v_mfma_f32_16x16x32_bf16 v[36:39], v[166:169], v[190:193], v[36:39]
	v_mfma_f32_16x16x32_bf16 v[32:35], v[174:177], v[190:193], v[32:35]
	v_mfma_f32_16x16x32_bf16 v[20:23], v[166:169], v[198:201], v[20:23]
	v_mfma_f32_16x16x32_bf16 v[16:19], v[174:177], v[198:201], v[16:19]
	v_mfma_f32_16x16x32_bf16 v[4:7], v[166:169], v[206:209], v[4:7]
	v_mfma_f32_16x16x32_bf16 v[0:3], v[174:177], v[206:209], v[0:3]
	v_mfma_f32_16x16x32_bf16 v[52:55], v[170:173], v[186:189], v[52:55]
	v_mfma_f32_16x16x32_bf16 v[48:51], v[178:181], v[186:189], v[48:51]
	v_mfma_f32_16x16x32_bf16 v[36:39], v[170:173], v[194:197], v[36:39]
	v_mfma_f32_16x16x32_bf16 v[32:35], v[178:181], v[194:197], v[32:35]
	v_mfma_f32_16x16x32_bf16 v[20:23], v[170:173], v[202:205], v[20:23]
	v_mfma_f32_16x16x32_bf16 v[16:19], v[178:181], v[202:205], v[16:19]
	v_mfma_f32_16x16x32_bf16 v[4:7], v[170:173], v[210:213], v[4:7]
	v_mfma_f32_16x16x32_bf16 v[0:3], v[178:181], v[210:213], v[0:3]
	s_setprio 0
	s_barrier
; #define PG8_STAGE(bufoff, gbase, voff) do { _Pragma("unroll") for (int _i = 0; _i < 2; ++_i) \
;         __builtin_amdgcn_global_load_lds((const unsigned*)((const char*)(gbase) + (voff)[_i]), (LAS unsigned*)(lds + (bufoff) + ldsw + _i * 8192), 16, 0, 0); } while (0)
; #define PG8_LDA(dst, b, h) do { _Pragma("unroll") for (int m = 0; m < 4; ++m) _Pragma("unroll") for (int k = 0; k < 2; ++k) dst[m][k] = *(const LAS bf16x8*)(lds + PG8_SA(b, h) + aoff + m * 2048 + k * 1024); } while (0)
; #define PG8_LDB(dst, b, h) do { _Pragma("unroll") for (int n = 0; n < 2; ++n) _Pragma("unroll") for (int k = 0; k < 2; ++k) dst[n][k] = *(const LAS bf16x8*)(lds + PG8_SB(b, h) + boff + n * 2048 + k * 1024); } while (0)
; #define PG8_MMA(ai, bj, At, Bt) do { __builtin_amdgcn_s_setprio(1); _Pragma("unroll") for (int m = 0; m < 4; ++m) _Pragma("unroll") for (int n = 0; n < 2; ++n) _Pragma("unroll") for (int k = 0; k < 2; ++k) \
;         acc[ai][bj][m][n] = __builtin_amdgcn_mfma_f32_16x16x32_bf16(Bt[n][k], At[m][k], acc[ai][bj][m][n], 0, 0, 0); __builtin_amdgcn_s_setprio(0); } while (0)
; #define PG8_WAIT_V(n) asm volatile("s_waitcnt vmcnt(" #n ")" ::: "memory")
; #define PG8_WAIT_L(n) asm volatile("s_waitcnt lgkmcnt(" #n ")" ::: "memory")
; #define PG8_BAR __builtin_amdgcn_s_barrier()
; #define PG8_SCHED __builtin_amdgcn_sched_barrier(0)
; template <class Epi, bool ALIGN_EPI, int K, int LDA, int LDB>
; __device__ __forceinline__ void gemm_phase(LAS unsigned char* lds, const int wid, const Gemm g, const StaticOrder& S, const Epi& E) {
;     ...
;             PG8_LDB(B0, 1, 0); PG8_LDB(B1, 1, 1); PG8_SCHED; PG8_LDA(At, 1, 0); PG8_STAGE(PG8_SA(0, 1), a2 + hA, voffA);
;             PG8_WAIT_V(8); PG8_WAIT_L(0); PG8_BAR; PG8_MMA(0, 0, At, B0); PG8_MMA(0, 1, At, B1); PG8_BAR; PG8_SCHED;
;             PG8_LDA(At, 1, 1); PG8_STAGE(PG8_SB(1, 0), b3, voffB); PG8_STAGE(PG8_SB(1, 1), b3 + hB, voffB); PG8_STAGE(PG8_SA(1, 0), a3, voffA);
;             PG8_WAIT_V(8); PG8_WAIT_L(0); PG8_BAR; PG8_MMA(1, 0, At, B0); PG8_MMA(1, 1, At, B1); PG8_BAR; PG8_SCHED;
;         }
;         if constexpr (ALIGN_EPI) { if (wr == 0) PG8_BAR; }
	s_add_i32 s52, 0, 0x18000
	s_add_i32 s53, 0, 0x1c000
	v_add_u32_e32 v162, s52, v150
	v_add_u32_e32 v178, s53, v150
	ds_read_b128 v[144:147], v162
	ds_read_b128 v[154:157], v162 offset:1024
	ds_read_b128 v[158:161], v162 offset:2048
	ds_read_b128 v[162:165], v162 offset:3072
	ds_read_b128 v[166:169], v178
	ds_read_b128 v[170:173], v178 offset:1024
	ds_read_b128 v[174:177], v178 offset:2048
	ds_read_b128 v[178:181], v178 offset:3072
	s_add_u32 s38, s38, 0x40000
	s_addc_u32 s39, s39, 0
	s_mov_b32 m0, s40
	ds_read_b128 v[182:185], v153 offset:32768
	ds_read_b128 v[186:189], v153 offset:33792
	ds_read_b128 v[190:193], v153 offset:34816
	ds_read_b128 v[194:197], v153 offset:35840
	ds_read_b128 v[198:201], v153 offset:36864
	ds_read_b128 v[202:205], v153 offset:37888
	ds_read_b128 v[206:209], v153 offset:38912
	ds_read_b128 v[210:213], v153 offset:39936
	global_load_lds_dwordx4 v128, s[38:39]
	s_mov_b32 m0, s41
	s_nop 0
	global_load_lds_dwordx4 v132, s[38:39]
	s_waitcnt vmcnt(8)
	s_waitcnt lgkmcnt(0)
	s_barrier
	s_setprio 1
	s_waitcnt lgkmcnt(0)
	v_mfma_f32_16x16x32_bf16 v[124:127], v[144:147], v[182:185], v[124:127]
	v_mfma_f32_16x16x32_bf16 v[120:123], v[158:161], v[182:185], v[120:123]
	v_mfma_f32_16x16x32_bf16 v[108:111], v[144:147], v[190:193], v[108:111]
	v_mfma_f32_16x16x32_bf16 v[104:107], v[158:161], v[190:193], v[104:107]
	v_mfma_f32_16x16x32_bf16 v[92:95], v[144:147], v[198:201], v[92:95]
	v_mfma_f32_16x16x32_bf16 v[88:91], v[158:161], v[198:201], v[88:91]
	v_mfma_f32_16x16x32_bf16 v[76:79], v[144:147], v[206:209], v[76:79]
	v_mfma_f32_16x16x32_bf16 v[72:75], v[158:161], v[206:209], v[72:75]
	v_mfma_f32_16x16x32_bf16 v[124:127], v[154:157], v[186:189], v[124:127]
	v_mfma_f32_16x16x32_bf16 v[120:123], v[162:165], v[186:189], v[120:123]
	v_mfma_f32_16x16x32_bf16 v[108:111], v[154:157], v[194:197], v[108:111]
	v_mfma_f32_16x16x32_bf16 v[104:107], v[162:165], v[194:197], v[104:107]
	v_mfma_f32_16x16x32_bf16 v[92:95], v[154:157], v[202:205], v[92:95]
	v_mfma_f32_16x16x32_bf16 v[88:91], v[162:165], v[202:205], v[88:91]
	v_mfma_f32_16x16x32_bf16 v[76:79], v[154:157], v[210:213], v[76:79]
	v_mfma_f32_16x16x32_bf16 v[72:75], v[162:165], v[210:213], v[72:75]
	s_setprio 0
	s_setprio 1
	v_mfma_f32_16x16x32_bf16 v[116:119], v[166:169], v[182:185], v[116:119]
	v_mfma_f32_16x16x32_bf16 v[112:115], v[174:177], v[182:185], v[112:115]
	v_mfma_f32_16x16x32_bf16 v[100:103], v[166:169], v[190:193], v[100:103]
	v_mfma_f32_16x16x32_bf16 v[96:99], v[174:177], v[190:193], v[96:99]
	v_mfma_f32_16x16x32_bf16 v[84:87], v[166:169], v[198:201], v[84:87]
	v_mfma_f32_16x16x32_bf16 v[80:83], v[174:177], v[198:201], v[80:83]
	v_mfma_f32_16x16x32_bf16 v[68:71], v[166:169], v[206:209], v[68:71]
	v_mfma_f32_16x16x32_bf16 v[64:67], v[174:177], v[206:209], v[64:67]
	v_mfma_f32_16x16x32_bf16 v[116:119], v[170:173], v[186:189], v[116:119]
	v_mfma_f32_16x16x32_bf16 v[112:115], v[178:181], v[186:189], v[112:115]
	v_mfma_f32_16x16x32_bf16 v[100:103], v[170:173], v[194:197], v[100:103]
	v_mfma_f32_16x16x32_bf16 v[96:99], v[178:181], v[194:197], v[96:99]
	v_mfma_f32_16x16x32_bf16 v[84:87], v[170:173], v[202:205], v[84:87]
	v_mfma_f32_16x16x32_bf16 v[80:83], v[178:181], v[202:205], v[80:83]
	v_mfma_f32_16x16x32_bf16 v[68:71], v[170:173], v[210:213], v[68:71]
	v_mfma_f32_16x16x32_bf16 v[64:67], v[178:181], v[210:213], v[64:67]
	s_setprio 0
	s_barrier
	s_add_i32 s38, s52, s3
	s_mov_b32 m0, s38
	ds_read_b128 v[182:185], v153 offset:49152
	ds_read_b128 v[186:189], v153 offset:50176
	ds_read_b128 v[190:193], v153 offset:51200
	ds_read_b128 v[194:197], v153 offset:52224
	ds_read_b128 v[198:201], v153 offset:53248
	ds_read_b128 v[202:205], v153 offset:54272
	ds_read_b128 v[206:209], v153 offset:55296
	ds_read_b128 v[210:213], v153 offset:56320
	global_load_lds_dwordx4 v130, s[98:99]
	s_add_i32 m0, s38, 0x2000
	s_add_u32 s36, s36, 0x40080
	s_addc_u32 s37, s37, 0
	s_add_i32 s38, s53, s3
	global_load_lds_dwordx4 v134, s[98:99]
	s_mov_b32 m0, s38
	s_nop 0
	global_load_lds_dwordx4 v130, s[36:37]
	s_add_i32 m0, s38, 0x2000
	s_nop 0
	global_load_lds_dwordx4 v134, s[36:37]
	s_mov_b32 m0, s55
	s_nop 0
	global_load_lds_dwordx4 v128, s[100:101]
	s_mov_b32 m0, s56
	s_nop 0
	global_load_lds_dwordx4 v132, s[100:101]
	s_waitcnt vmcnt(8)
	s_waitcnt lgkmcnt(0)
	s_barrier
	s_setprio 1
	s_waitcnt lgkmcnt(0)
	v_mfma_f32_16x16x32_bf16 v[60:63], v[144:147], v[182:185], v[60:63]
	v_mfma_f32_16x16x32_bf16 v[56:59], v[158:161], v[182:185], v[56:59]
	v_mfma_f32_16x16x32_bf16 v[44:47], v[144:147], v[190:193], v[44:47]
	v_mfma_f32_16x16x32_bf16 v[40:43], v[158:161], v[190:193], v[40:43]
	v_mfma_f32_16x16x32_bf16 v[28:31], v[144:147], v[198:201], v[28:31]
	v_mfma_f32_16x16x32_bf16 v[24:27], v[158:161], v[198:201], v[24:27]
	v_mfma_f32_16x16x32_bf16 v[12:15], v[144:147], v[206:209], v[12:15]
	v_mfma_f32_16x16x32_bf16 v[8:11], v[158:161], v[206:209], v[8:11]
	v_mfma_f32_16x16x32_bf16 v[60:63], v[154:157], v[186:189], v[60:63]
	v_mfma_f32_16x16x32_bf16 v[56:59], v[162:165], v[186:189], v[56:59]
	v_mfma_f32_16x16x32_bf16 v[44:47], v[154:157], v[194:197], v[44:47]
	v_mfma_f32_16x16x32_bf16 v[40:43], v[162:165], v[194:197], v[40:43]
	v_mfma_f32_16x16x32_bf16 v[28:31], v[154:157], v[202:205], v[28:31]
	v_mfma_f32_16x16x32_bf16 v[24:27], v[162:165], v[202:205], v[24:27]
	v_mfma_f32_16x16x32_bf16 v[12:15], v[154:157], v[210:213], v[12:15]
	v_mfma_f32_16x16x32_bf16 v[8:11], v[162:165], v[210:213], v[8:11]
	s_setprio 0
	s_setprio 1
	v_mfma_f32_16x16x32_bf16 v[52:55], v[166:169], v[182:185], v[52:55]
	v_mfma_f32_16x16x32_bf16 v[48:51], v[174:177], v[182:185], v[48:51]
	v_mfma_f32_16x16x32_bf16 v[36:39], v[166:169], v[190:193], v[36:39]
	v_mfma_f32_16x16x32_bf16 v[32:35], v[174:177], v[190:193], v[32:35]
	v_mfma_f32_16x16x32_bf16 v[20:23], v[166:169], v[198:201], v[20:23]
	v_mfma_f32_16x16x32_bf16 v[16:19], v[174:177], v[198:201], v[16:19]
	v_mfma_f32_16x16x32_bf16 v[4:7], v[166:169], v[206:209], v[4:7]
	v_mfma_f32_16x16x32_bf16 v[0:3], v[174:177], v[206:209], v[0:3]
	v_mfma_f32_16x16x32_bf16 v[52:55], v[170:173], v[186:189], v[52:55]
	v_mfma_f32_16x16x32_bf16 v[48:51], v[178:181], v[186:189], v[48:51]
	v_mfma_f32_16x16x32_bf16 v[36:39], v[170:173], v[194:197], v[36:39]
	v_mfma_f32_16x16x32_bf16 v[32:35], v[178:181], v[194:197], v[32:35]
	v_mfma_f32_16x16x32_bf16 v[20:23], v[170:173], v[202:205], v[20:23]
	v_mfma_f32_16x16x32_bf16 v[16:19], v[178:181], v[202:205], v[16:19]
	v_mfma_f32_16x16x32_bf16 v[4:7], v[170:173], v[210:213], v[4:7]
	v_mfma_f32_16x16x32_bf16 v[0:3], v[178:181], v[210:213], v[0:3]
	s_setprio 0
	s_barrier
	s_add_i32 s61, s61, 2
	s_add_u32 s34, s34, 0x100
	s_addc_u32 s35, s35, 0
	s_add_u32 s59, s59, 0x100
	s_addc_u32 s60, s60, 0
	s_cmp_gt_u32 s61, 13
	s_cbranch_scc0 .LBB0_1279
	s_and_b64 vcc, exec, s[10:11]
	s_cbranch_vccz .LBB0_1282
	s_barrier

; #define PG8_STAGE(bufoff, gbase, voff) do { _Pragma("unroll") for (int _i = 0; _i < 2; ++_i) \
;         __builtin_amdgcn_global_load_lds((const unsigned*)((const char*)(gbase) + (voff)[_i]), (LAS unsigned*)(lds + (bufoff) + ldsw + _i * 8192), 16, 0, 0); } while (0)
; #define PG8_LDA(dst, b, h) do { _Pragma("unroll") for (int m = 0; m < 4; ++m) _Pragma("unroll") for (int k = 0; k < 2; ++k) dst[m][k] = *(const LAS bf16x8*)(lds + PG8_SA(b, h) + aoff + m * 2048 + k * 1024); } while (0)
; #define PG8_LDB(dst, b, h) do { _Pragma("unroll") for (int n = 0; n < 2; ++n) _Pragma("unroll") for (int k = 0; k < 2; ++k) dst[n][k] = *(const LAS bf16x8*)(lds + PG8_SB(b, h) + boff + n * 2048 + k * 1024); } while (0)
; #define PG8_MMA(ai, bj, At, Bt) do { __builtin_amdgcn_s_setprio(1); _Pragma("unroll") for (int m = 0; m < 4; ++m) _Pragma("unroll") for (int n = 0; n < 2; ++n) _Pragma("unroll") for (int k = 0; k < 2; ++k) \
;         acc[ai][bj][m][n] = __builtin_amdgcn_mfma_f32_16x16x32_bf16(Bt[n][k], At[m][k], acc[ai][bj][m][n], 0, 0, 0); __builtin_amdgcn_s_setprio(0); } while (0)
; #define PG8_WAIT_V(n) asm volatile("s_waitcnt vmcnt(" #n ")" ::: "memory")
; #define PG8_WAIT_L(n) asm volatile("s_waitcnt lgkmcnt(" #n ")" ::: "memory")
; #define PG8_BAR __builtin_amdgcn_s_barrier()
; #define PG8_SCHED __builtin_amdgcn_sched_barrier(0)
; template <class Epi, bool ALIGN_EPI, int K, int LDA, int LDB>
; __device__ __forceinline__ void gemm_phase(LAS unsigned char* lds, const int wid, const Gemm g, const StaticOrder& S, const Epi& E) {
;     ...
;             const bool last = (t == nt - 2);
;             const char* a1 = cA + (size_t)(t + 1) * kstep;
;             const char* a2 = last ? nA : cA + (size_t)(t + 2) * kstep; const char* b2 = last ? nB : cB + (size_t)(t + 2) * kstep;
;             const char* a3 = a2 + kstep; const char* b3 = b2 + kstep;
;             PG8_LDB(B0, 0, 0); PG8_LDB(B1, 0, 1); PG8_SCHED; PG8_LDA(At, 0, 0); PG8_STAGE(PG8_SA(1, 1), a1 + hA, voffA);
;             PG8_WAIT_V(8); PG8_WAIT_L(0); PG8_BAR; PG8_MMA(0, 0, At, B0); PG8_MMA(0, 1, At, B1); PG8_BAR; PG8_SCHED;
;             PG8_LDA(At, 0, 1); PG8_STAGE(PG8_SB(0, 0), b2, voffB); PG8_STAGE(PG8_SB(0, 1), b2 + hB, voffB); PG8_STAGE(PG8_SA(0, 0), a2, voffA);
;             PG8_WAIT_V(8); PG8_WAIT_L(0); PG8_BAR; PG8_MMA(1, 0, At, B0); PG8_MMA(1, 1, At, B1); PG8_BAR; PG8_SCHED;
.LBB0_1477:
	ds_read_b128 v[128:131], v175
	ds_read_b128 v[132:135], v175 offset:1024
	ds_read_b128 v[136:139], v175 offset:2048
	ds_read_b128 v[140:143], v175 offset:3072
	ds_read_b128 v[144:147], v176
	ds_read_b128 v[164:167], v176 offset:1024
	ds_read_b128 v[168:171], v176 offset:2048
	ds_read_b128 v[178:181], v176 offset:3072
	s_add_u32 s36, s34, 0xfffc0080
	s_addc_u32 s37, s35, -1
	s_cmp_eq_u32 s69, 12
	s_cselect_b32 s39, s25, s37
	s_cselect_b32 s38, s42, s36
	s_cselect_b32 s37, s23, s68
	s_cselect_b32 s36, s66, s67
	s_add_i32 m0, s40, 0xc000
	ds_read_b128 v[182:185], v177
	ds_read_b128 v[186:189], v177 offset:1024
	ds_read_b128 v[190:193], v177 offset:2048
	ds_read_b128 v[194:197], v177 offset:3072
	ds_read_b128 v[198:201], v177 offset:4096
	ds_read_b128 v[202:205], v177 offset:5120
	ds_read_b128 v[206:209], v177 offset:6144
	ds_read_b128 v[210:213], v177 offset:7168
	global_load_lds_dwordx4 v156, s[34:35]
	s_add_i32 m0, s40, 0xe000
	s_nop 0
	global_load_lds_dwordx4 v158, s[34:35]
	s_waitcnt vmcnt(8)
	s_waitcnt lgkmcnt(0)
	s_barrier
	s_setprio 1
	s_waitcnt lgkmcnt(0)
	v_mfma_f32_16x16x32_bf16 v[124:127], v[128:131], v[182:185], v[124:127]
	v_mfma_f32_16x16x32_bf16 v[116:119], v[136:139], v[182:185], v[116:119]
	v_mfma_f32_16x16x32_bf16 v[120:123], v[128:131], v[190:193], v[120:123]
	v_mfma_f32_16x16x32_bf16 v[112:115], v[136:139], v[190:193], v[112:115]
	v_mfma_f32_16x16x32_bf16 v[92:95], v[128:131], v[198:201], v[92:95]
	v_mfma_f32_16x16x32_bf16 v[88:91], v[136:139], v[198:201], v[88:91]
	v_mfma_f32_16x16x32_bf16 v[76:79], v[128:131], v[206:209], v[76:79]
	v_mfma_f32_16x16x32_bf16 v[72:75], v[136:139], v[206:209], v[72:75]
	v_mfma_f32_16x16x32_bf16 v[124:127], v[132:135], v[186:189], v[124:127]
	v_mfma_f32_16x16x32_bf16 v[116:119], v[140:143], v[186:189], v[116:119]
	v_mfma_f32_16x16x32_bf16 v[120:123], v[132:135], v[194:197], v[120:123]
	v_mfma_f32_16x16x32_bf16 v[112:115], v[140:143], v[194:197], v[112:115]
	v_mfma_f32_16x16x32_bf16 v[92:95], v[132:135], v[202:205], v[92:95]
	v_mfma_f32_16x16x32_bf16 v[88:91], v[140:143], v[202:205], v[88:91]
	v_mfma_f32_16x16x32_bf16 v[76:79], v[132:135], v[210:213], v[76:79]
	v_mfma_f32_16x16x32_bf16 v[72:75], v[140:143], v[210:213], v[72:75]
	s_setprio 0
	s_setprio 1
	v_mfma_f32_16x16x32_bf16 v[108:111], v[144:147], v[182:185], v[108:111]
	v_mfma_f32_16x16x32_bf16 v[104:107], v[168:171], v[182:185], v[104:107]
	v_mfma_f32_16x16x32_bf16 v[100:103], v[144:147], v[190:193], v[100:103]
	v_mfma_f32_16x16x32_bf16 v[96:99], v[168:171], v[190:193], v[96:99]
	v_mfma_f32_16x16x32_bf16 v[84:87], v[144:147], v[198:201], v[84:87]
	v_mfma_f32_16x16x32_bf16 v[80:83], v[168:171], v[198:201], v[80:83]
	v_mfma_f32_16x16x32_bf16 v[68:71], v[144:147], v[206:209], v[68:71]
	v_mfma_f32_16x16x32_bf16 v[64:67], v[168:171], v[206:209], v[64:67]
	v_mfma_f32_16x16x32_bf16 v[108:111], v[164:167], v[186:189], v[108:111]
	v_mfma_f32_16x16x32_bf16 v[104:107], v[178:181], v[186:189], v[104:107]
	v_mfma_f32_16x16x32_bf16 v[100:103], v[164:167], v[194:197], v[100:103]
	v_mfma_f32_16x16x32_bf16 v[96:99], v[178:181], v[194:197], v[96:99]
	v_mfma_f32_16x16x32_bf16 v[84:87], v[164:167], v[202:205], v[84:87]
	v_mfma_f32_16x16x32_bf16 v[80:83], v[178:181], v[202:205], v[80:83]
	v_mfma_f32_16x16x32_bf16 v[68:71], v[164:167], v[210:213], v[68:71]
	v_mfma_f32_16x16x32_bf16 v[64:67], v[178:181], v[210:213], v[64:67]
	s_setprio 0
	s_barrier
	s_add_u32 s98, s36, s12
	s_addc_u32 s99, s37, s13
	s_add_u32 s100, s38, s12
	s_addc_u32 s101, s39, s13
	s_add_i32 s52, s58, s33
	s_mov_b32 m0, s52
	ds_read_b128 v[182:185], v177 offset:16384
	ds_read_b128 v[186:189], v177 offset:17408
	ds_read_b128 v[190:193], v177 offset:18432
	ds_read_b128 v[194:197], v177 offset:19456
	ds_read_b128 v[198:201], v177 offset:20480
	ds_read_b128 v[202:205], v177 offset:21504
	ds_read_b128 v[206:209], v177 offset:22528
	ds_read_b128 v[210:213], v177 offset:23552
	global_load_lds_dwordx4 v150, s[36:37]
	s_add_i32 m0, s52, 0x2000
	s_add_u32 s70, s36, 0x40000
	s_addc_u32 s71, s37, 0
	s_add_i32 s52, s59, s33
	global_load_lds_dwordx4 v154, s[36:37]
	s_mov_b32 m0, s52
	s_nop 0
	global_load_lds_dwordx4 v150, s[70:71]
	s_add_i32 m0, s52, 0x2000
	s_nop 0
	global_load_lds_dwordx4 v154, s[70:71]
	s_mov_b32 m0, s40
	s_nop 0
	global_load_lds_dwordx4 v148, s[38:39]
	s_mov_b32 m0, s41
	s_nop 0
	global_load_lds_dwordx4 v152, s[38:39]
	s_waitcnt vmcnt(8)
	s_waitcnt lgkmcnt(0)
	s_barrier
	s_setprio 1
	s_waitcnt lgkmcnt(0)
	v_mfma_f32_16x16x32_bf16 v[60:63], v[128:131], v[182:185], v[60:63]
	v_mfma_f32_16x16x32_bf16 v[56:59], v[136:139], v[182:185], v[56:59]
	v_mfma_f32_16x16x32_bf16 v[44:47], v[128:131], v[190:193], v[44:47]
	v_mfma_f32_16x16x32_bf16 v[40:43], v[136:139], v[190:193], v[40:43]
	v_mfma_f32_16x16x32_bf16 v[36:39], v[128:131], v[198:201], v[36:39]
	v_mfma_f32_16x16x32_bf16 v[32:35], v[136:139], v[198:201], v[32:35]
	v_mfma_f32_16x16x32_bf16 v[20:23], v[128:131], v[206:209], v[20:23]
	v_mfma_f32_16x16x32_bf16 v[16:19], v[136:139], v[206:209], v[16:19]
	v_mfma_f32_16x16x32_bf16 v[60:63], v[132:135], v[186:189], v[60:63]
	v_mfma_f32_16x16x32_bf16 v[56:59], v[140:143], v[186:189], v[56:59]
	v_mfma_f32_16x16x32_bf16 v[44:47], v[132:135], v[194:197], v[44:47]
	v_mfma_f32_16x16x32_bf16 v[40:43], v[140:143], v[194:197], v[40:43]
	v_mfma_f32_16x16x32_bf16 v[36:39], v[132:135], v[202:205], v[36:39]
	v_mfma_f32_16x16x32_bf16 v[32:35], v[140:143], v[202:205], v[32:35]
	v_mfma_f32_16x16x32_bf16 v[20:23], v[132:135], v[210:213], v[20:23]
	v_mfma_f32_16x16x32_bf16 v[16:19], v[140:143], v[210:213], v[16:19]
	s_setprio 0
	s_setprio 1
	v_mfma_f32_16x16x32_bf16 v[52:55], v[144:147], v[182:185], v[52:55]
	v_mfma_f32_16x16x32_bf16 v[48:51], v[168:171], v[182:185], v[48:51]
	v_mfma_f32_16x16x32_bf16 v[28:31], v[144:147], v[190:193], v[28:31]
	v_mfma_f32_16x16x32_bf16 v[24:27], v[168:171], v[190:193], v[24:27]
	v_mfma_f32_16x16x32_bf16 v[12:15], v[144:147], v[198:201], v[12:15]
	v_mfma_f32_16x16x32_bf16 v[8:11], v[168:171], v[198:201], v[8:11]
	v_mfma_f32_16x16x32_bf16 v[4:7], v[144:147], v[206:209], v[4:7]
	v_mfma_f32_16x16x32_bf16 v[0:3], v[168:171], v[206:209], v[0:3]
	v_mfma_f32_16x16x32_bf16 v[52:55], v[164:167], v[186:189], v[52:55]
	v_mfma_f32_16x16x32_bf16 v[48:51], v[178:181], v[186:189], v[48:51]
	v_mfma_f32_16x16x32_bf16 v[28:31], v[164:167], v[194:197], v[28:31]
	v_mfma_f32_16x16x32_bf16 v[24:27], v[178:181], v[194:197], v[24:27]
	v_mfma_f32_16x16x32_bf16 v[12:15], v[164:167], v[202:205], v[12:15]
	v_mfma_f32_16x16x32_bf16 v[8:11], v[178:181], v[202:205], v[8:11]
	v_mfma_f32_16x16x32_bf16 v[4:7], v[164:167], v[210:213], v[4:7]
	v_mfma_f32_16x16x32_bf16 v[0:3], v[178:181], v[210:213], v[0:3]
	s_setprio 0
	s_barrier
; #define PG8_STAGE(bufoff, gbase, voff) do { _Pragma("unroll") for (int _i = 0; _i < 2; ++_i) \
;         __builtin_amdgcn_global_load_lds((const unsigned*)((const char*)(gbase) + (voff)[_i]), (LAS unsigned*)(lds + (bufoff) + ldsw + _i * 8192), 16, 0, 0); } while (0)
; #define PG8_LDA(dst, b, h) do { _Pragma("unroll") for (int m = 0; m < 4; ++m) _Pragma("unroll") for (int k = 0; k < 2; ++k) dst[m][k] = *(const LAS bf16x8*)(lds + PG8_SA(b, h) + aoff + m * 2048 + k * 1024); } while (0)
; #define PG8_LDB(dst, b, h) do { _Pragma("unroll") for (int n = 0; n < 2; ++n) _Pragma("unroll") for (int k = 0; k < 2; ++k) dst[n][k] = *(const LAS bf16x8*)(lds + PG8_SB(b, h) + boff + n * 2048 + k * 1024); } while (0)
; #define PG8_MMA(ai, bj, At, Bt) do { __builtin_amdgcn_s_setprio(1); _Pragma("unroll") for (int m = 0; m < 4; ++m) _Pragma("unroll") for (int n = 0; n < 2; ++n) _Pragma("unroll") for (int k = 0; k < 2; ++k) \
;         acc[ai][bj][m][n] = __builtin_amdgcn_mfma_f32_16x16x32_bf16(Bt[n][k], At[m][k], acc[ai][bj][m][n], 0, 0, 0); __builtin_amdgcn_s_setprio(0); } while (0)
; #define PG8_WAIT_V(n) asm volatile("s_waitcnt vmcnt(" #n ")" ::: "memory")
; #define PG8_WAIT_L(n) asm volatile("s_waitcnt lgkmcnt(" #n ")" ::: "memory")
; #define PG8_BAR __builtin_amdgcn_s_barrier()
; #define PG8_SCHED __builtin_amdgcn_sched_barrier(0)
; template <class Epi, bool ALIGN_EPI, int K, int LDA, int LDB>
; __device__ __forceinline__ void gemm_phase(LAS unsigned char* lds, const int wid, const Gemm g, const StaticOrder& S, const Epi& E) {
;     ...
;             PG8_LDB(B0, 1, 0); PG8_LDB(B1, 1, 1); PG8_SCHED; PG8_LDA(At, 1, 0); PG8_STAGE(PG8_SA(0, 1), a2 + hA, voffA);
;             PG8_WAIT_V(8); PG8_WAIT_L(0); PG8_BAR; PG8_MMA(0, 0, At, B0); PG8_MMA(0, 1, At, B1); PG8_BAR; PG8_SCHED;
;             PG8_LDA(At, 1, 1); PG8_STAGE(PG8_SB(1, 0), b3, voffB); PG8_STAGE(PG8_SB(1, 1), b3 + hB, voffB); PG8_STAGE(PG8_SA(1, 0), a3, voffA);
;             PG8_WAIT_V(8); PG8_WAIT_L(0); PG8_BAR; PG8_MMA(1, 0, At, B0); PG8_MMA(1, 1, At, B1); PG8_BAR; PG8_SCHED;
;         }
;         if constexpr (ALIGN_EPI) { if (wr == 0) PG8_BAR; }
	s_add_i32 s52, 0, 0x18000
	s_add_i32 s53, 0, 0x1c000
	v_add_u32_e32 v140, s52, v174
	v_add_u32_e32 v178, s53, v174
	ds_read_b128 v[128:131], v140
	ds_read_b128 v[132:135], v140 offset:1024
	ds_read_b128 v[136:139], v140 offset:2048
	ds_read_b128 v[140:143], v140 offset:3072
	ds_read_b128 v[144:147], v178
	ds_read_b128 v[164:167], v178 offset:1024
	ds_read_b128 v[168:171], v178 offset:2048
	ds_read_b128 v[178:181], v178 offset:3072
	s_add_u32 s38, s38, 0x40000
	s_addc_u32 s39, s39, 0
	s_mov_b32 m0, s43
	ds_read_b128 v[182:185], v177 offset:32768
	ds_read_b128 v[186:189], v177 offset:33792
	ds_read_b128 v[190:193], v177 offset:34816
	ds_read_b128 v[194:197], v177 offset:35840
	ds_read_b128 v[198:201], v177 offset:36864
	ds_read_b128 v[202:205], v177 offset:37888
	ds_read_b128 v[206:209], v177 offset:38912
	ds_read_b128 v[210:213], v177 offset:39936
	global_load_lds_dwordx4 v148, s[38:39]
	s_mov_b32 m0, s48
	s_nop 0
	global_load_lds_dwordx4 v152, s[38:39]
	s_waitcnt vmcnt(8)
	s_waitcnt lgkmcnt(0)
	s_barrier
	s_setprio 1
	s_waitcnt lgkmcnt(0)
	v_mfma_f32_16x16x32_bf16 v[124:127], v[128:131], v[182:185], v[124:127]
	v_mfma_f32_16x16x32_bf16 v[116:119], v[136:139], v[182:185], v[116:119]
	v_mfma_f32_16x16x32_bf16 v[120:123], v[128:131], v[190:193], v[120:123]
	v_mfma_f32_16x16x32_bf16 v[112:115], v[136:139], v[190:193], v[112:115]
	v_mfma_f32_16x16x32_bf16 v[92:95], v[128:131], v[198:201], v[92:95]
	v_mfma_f32_16x16x32_bf16 v[88:91], v[136:139], v[198:201], v[88:91]
	v_mfma_f32_16x16x32_bf16 v[76:79], v[128:131], v[206:209], v[76:79]
	v_mfma_f32_16x16x32_bf16 v[72:75], v[136:139], v[206:209], v[72:75]
	v_mfma_f32_16x16x32_bf16 v[124:127], v[132:135], v[186:189], v[124:127]
	v_mfma_f32_16x16x32_bf16 v[116:119], v[140:143], v[186:189], v[116:119]
	v_mfma_f32_16x16x32_bf16 v[120:123], v[132:135], v[194:197], v[120:123]
	v_mfma_f32_16x16x32_bf16 v[112:115], v[140:143], v[194:197], v[112:115]
	v_mfma_f32_16x16x32_bf16 v[92:95], v[132:135], v[202:205], v[92:95]
	v_mfma_f32_16x16x32_bf16 v[88:91], v[140:143], v[202:205], v[88:91]
	v_mfma_f32_16x16x32_bf16 v[76:79], v[132:135], v[210:213], v[76:79]
	v_mfma_f32_16x16x32_bf16 v[72:75], v[140:143], v[210:213], v[72:75]
	s_setprio 0
	s_setprio 1
	v_mfma_f32_16x16x32_bf16 v[108:111], v[144:147], v[182:185], v[108:111]
	v_mfma_f32_16x16x32_bf16 v[104:107], v[168:171], v[182:185], v[104:107]
	v_mfma_f32_16x16x32_bf16 v[100:103], v[144:147], v[190:193], v[100:103]
	v_mfma_f32_16x16x32_bf16 v[96:99], v[168:171], v[190:193], v[96:99]
	v_mfma_f32_16x16x32_bf16 v[84:87], v[144:147], v[198:201], v[84:87]
	v_mfma_f32_16x16x32_bf16 v[80:83], v[168:171], v[198:201], v[80:83]
	v_mfma_f32_16x16x32_bf16 v[68:71], v[144:147], v[206:209], v[68:71]
	v_mfma_f32_16x16x32_bf16 v[64:67], v[168:171], v[206:209], v[64:67]
	v_mfma_f32_16x16x32_bf16 v[108:111], v[164:167], v[186:189], v[108:111]
	v_mfma_f32_16x16x32_bf16 v[104:107], v[178:181], v[186:189], v[104:107]
	v_mfma_f32_16x16x32_bf16 v[100:103], v[164:167], v[194:197], v[100:103]
	v_mfma_f32_16x16x32_bf16 v[96:99], v[178:181], v[194:197], v[96:99]
	v_mfma_f32_16x16x32_bf16 v[84:87], v[164:167], v[202:205], v[84:87]
	v_mfma_f32_16x16x32_bf16 v[80:83], v[178:181], v[202:205], v[80:83]
	v_mfma_f32_16x16x32_bf16 v[68:71], v[164:167], v[210:213], v[68:71]
	v_mfma_f32_16x16x32_bf16 v[64:67], v[178:181], v[210:213], v[64:67]
	s_setprio 0
	s_barrier
	s_add_i32 s38, s52, s33
	s_mov_b32 m0, s38
	ds_read_b128 v[182:185], v177 offset:49152
	ds_read_b128 v[186:189], v177 offset:50176
	ds_read_b128 v[190:193], v177 offset:51200
	ds_read_b128 v[194:197], v177 offset:52224
	ds_read_b128 v[198:201], v177 offset:53248
	ds_read_b128 v[202:205], v177 offset:54272
	ds_read_b128 v[206:209], v177 offset:55296
	ds_read_b128 v[210:213], v177 offset:56320
	global_load_lds_dwordx4 v150, s[98:99]
	s_add_i32 m0, s38, 0x2000
	s_add_u32 s36, s36, 0x40080
	s_addc_u32 s37, s37, 0
	s_add_i32 s38, s53, s33
	global_load_lds_dwordx4 v154, s[98:99]
	s_mov_b32 m0, s38
	s_nop 0
	global_load_lds_dwordx4 v150, s[36:37]
	s_add_i32 m0, s38, 0x2000
	s_nop 0
	global_load_lds_dwordx4 v154, s[36:37]
	s_mov_b32 m0, s55
	s_nop 0
	global_load_lds_dwordx4 v148, s[100:101]
	s_mov_b32 m0, s56
	s_nop 0
	global_load_lds_dwordx4 v152, s[100:101]
	s_waitcnt vmcnt(8)
	s_waitcnt lgkmcnt(0)
	s_barrier
	s_setprio 1
	s_waitcnt lgkmcnt(0)
	v_mfma_f32_16x16x32_bf16 v[60:63], v[128:131], v[182:185], v[60:63]
	v_mfma_f32_16x16x32_bf16 v[56:59], v[136:139], v[182:185], v[56:59]
	v_mfma_f32_16x16x32_bf16 v[44:47], v[128:131], v[190:193], v[44:47]
	v_mfma_f32_16x16x32_bf16 v[40:43], v[136:139], v[190:193], v[40:43]
	v_mfma_f32_16x16x32_bf16 v[36:39], v[128:131], v[198:201], v[36:39]
	v_mfma_f32_16x16x32_bf16 v[32:35], v[136:139], v[198:201], v[32:35]
	v_mfma_f32_16x16x32_bf16 v[20:23], v[128:131], v[206:209], v[20:23]
	v_mfma_f32_16x16x32_bf16 v[16:19], v[136:139], v[206:209], v[16:19]
	v_mfma_f32_16x16x32_bf16 v[60:63], v[132:135], v[186:189], v[60:63]
	v_mfma_f32_16x16x32_bf16 v[56:59], v[140:143], v[186:189], v[56:59]
	v_mfma_f32_16x16x32_bf16 v[44:47], v[132:135], v[194:197], v[44:47]
	v_mfma_f32_16x16x32_bf16 v[40:43], v[140:143], v[194:197], v[40:43]
	v_mfma_f32_16x16x32_bf16 v[36:39], v[132:135], v[202:205], v[36:39]
	v_mfma_f32_16x16x32_bf16 v[32:35], v[140:143], v[202:205], v[32:35]
	v_mfma_f32_16x16x32_bf16 v[20:23], v[132:135], v[210:213], v[20:23]
	v_mfma_f32_16x16x32_bf16 v[16:19], v[140:143], v[210:213], v[16:19]
	s_setprio 0
	s_setprio 1
	v_mfma_f32_16x16x32_bf16 v[52:55], v[144:147], v[182:185], v[52:55]
	v_mfma_f32_16x16x32_bf16 v[48:51], v[168:171], v[182:185], v[48:51]
	v_mfma_f32_16x16x32_bf16 v[28:31], v[144:147], v[190:193], v[28:31]
	v_mfma_f32_16x16x32_bf16 v[24:27], v[168:171], v[190:193], v[24:27]
	v_mfma_f32_16x16x32_bf16 v[12:15], v[144:147], v[198:201], v[12:15]
	v_mfma_f32_16x16x32_bf16 v[8:11], v[168:171], v[198:201], v[8:11]
	v_mfma_f32_16x16x32_bf16 v[4:7], v[144:147], v[206:209], v[4:7]
	v_mfma_f32_16x16x32_bf16 v[0:3], v[168:171], v[206:209], v[0:3]
	v_mfma_f32_16x16x32_bf16 v[52:55], v[164:167], v[186:189], v[52:55]
	v_mfma_f32_16x16x32_bf16 v[48:51], v[178:181], v[186:189], v[48:51]
	v_mfma_f32_16x16x32_bf16 v[28:31], v[164:167], v[194:197], v[28:31]
	v_mfma_f32_16x16x32_bf16 v[24:27], v[178:181], v[194:197], v[24:27]
	v_mfma_f32_16x16x32_bf16 v[12:15], v[164:167], v[202:205], v[12:15]
	v_mfma_f32_16x16x32_bf16 v[8:11], v[178:181], v[202:205], v[8:11]
	v_mfma_f32_16x16x32_bf16 v[4:7], v[164:167], v[210:213], v[4:7]
	v_mfma_f32_16x16x32_bf16 v[0:3], v[178:181], v[210:213], v[0:3]
	s_setprio 0
	s_barrier
	s_add_i32 s69, s69, 2
	s_add_u32 s34, s34, 0x100
	s_addc_u32 s35, s35, 0
	s_add_u32 s67, s67, 0x100
	s_addc_u32 s68, s68, 0
	s_cmp_gt_u32 s69, 13
	s_cbranch_scc0 .LBB0_1477
	s_and_b64 vcc, exec, s[14:15]
	s_cbranch_vccz .LBB0_1480
	s_barrier

; #define PG8_STAGE(bufoff, gbase, voff) do { _Pragma("unroll") for (int _i = 0; _i < 2; ++_i) \
;         __builtin_amdgcn_global_load_lds((const unsigned*)((const char*)(gbase) + (voff)[_i]), (LAS unsigned*)(lds + (bufoff) + ldsw + _i * 8192), 16, 0, 0); } while (0)
; #define PG8_LDA(dst, b, h) do { _Pragma("unroll") for (int m = 0; m < 4; ++m) _Pragma("unroll") for (int k = 0; k < 2; ++k) dst[m][k] = *(const LAS bf16x8*)(lds + PG8_SA(b, h) + aoff + m * 2048 + k * 1024); } while (0)
; #define PG8_LDB(dst, b, h) do { _Pragma("unroll") for (int n = 0; n < 2; ++n) _Pragma("unroll") for (int k = 0; k < 2; ++k) dst[n][k] = *(const LAS bf16x8*)(lds + PG8_SB(b, h) + boff + n * 2048 + k * 1024); } while (0)
; #define PG8_MMA(ai, bj, At, Bt) do { __builtin_amdgcn_s_setprio(1); _Pragma("unroll") for (int m = 0; m < 4; ++m) _Pragma("unroll") for (int n = 0; n < 2; ++n) _Pragma("unroll") for (int k = 0; k < 2; ++k) \
;         acc[ai][bj][m][n] = __builtin_amdgcn_mfma_f32_16x16x32_bf16(Bt[n][k], At[m][k], acc[ai][bj][m][n], 0, 0, 0); __builtin_amdgcn_s_setprio(0); } while (0)
; #define PG8_WAIT_V(n) asm volatile("s_waitcnt vmcnt(" #n ")" ::: "memory")
; #define PG8_WAIT_L(n) asm volatile("s_waitcnt lgkmcnt(" #n ")" ::: "memory")
; #define PG8_BAR __builtin_amdgcn_s_barrier()
; #define PG8_SCHED __builtin_amdgcn_sched_barrier(0)
; template <class Epi, bool ALIGN_EPI, int K, int LDA, int LDB>
; __device__ __forceinline__ void gemm_phase(LAS unsigned char* lds, const int wid, const Gemm g, const StaticOrder& S, const Epi& E) {
;     ...
;             const bool last = (t == nt - 2);
;             const char* a1 = cA + (size_t)(t + 1) * kstep;
;             const char* a2 = last ? nA : cA + (size_t)(t + 2) * kstep; const char* b2 = last ? nB : cB + (size_t)(t + 2) * kstep;
;             const char* a3 = a2 + kstep; const char* b3 = b2 + kstep;
;             PG8_LDB(B0, 0, 0); PG8_LDB(B1, 0, 1); PG8_SCHED; PG8_LDA(At, 0, 0); PG8_STAGE(PG8_SA(1, 1), a1 + hA, voffA);
;             PG8_WAIT_V(8); PG8_WAIT_L(0); PG8_BAR; PG8_MMA(0, 0, At, B0); PG8_MMA(0, 1, At, B1); PG8_BAR; PG8_SCHED;
;             PG8_LDA(At, 0, 1); PG8_STAGE(PG8_SB(0, 0), b2, voffB); PG8_STAGE(PG8_SB(0, 1), b2 + hB, voffB); PG8_STAGE(PG8_SA(0, 0), a2, voffA);
;             PG8_WAIT_V(8); PG8_WAIT_L(0); PG8_BAR; PG8_MMA(1, 0, At, B0); PG8_MMA(1, 1, At, B1); PG8_BAR; PG8_SCHED;
.LBB0_1697:
	ds_read_b128 v[120:123], v167
	ds_read_b128 v[124:127], v167 offset:1024
	ds_read_b128 v[128:131], v167 offset:2048
	ds_read_b128 v[132:135], v167 offset:3072
	ds_read_b128 v[160:163], v168
	ds_read_b128 v[170:173], v168 offset:1024
	ds_read_b128 v[174:177], v168 offset:2048
	ds_read_b128 v[178:181], v168 offset:3072
	s_add_u32 s28, s26, 0x100
	s_addc_u32 s29, s27, 0
	s_cmp_eq_u32 s63, 40
	s_cselect_b32 s35, s7, s29
	s_cselect_b32 s34, s6, s28
	s_cselect_b32 s31, s25, s62
	s_cselect_b32 s30, s24, s61
	s_add_i32 m0, s36, 0xc000
	ds_read_b128 v[182:185], v169
	ds_read_b128 v[186:189], v169 offset:1024
	ds_read_b128 v[190:193], v169 offset:2048
	ds_read_b128 v[194:197], v169 offset:3072
	ds_read_b128 v[198:201], v169 offset:4096
	ds_read_b128 v[202:205], v169 offset:5120
	ds_read_b128 v[206:209], v169 offset:6144
	ds_read_b128 v[210:213], v169 offset:7168
	global_load_lds_dwordx4 v152, s[26:27]
	s_add_i32 m0, s36, 0xe000
	s_nop 0
	global_load_lds_dwordx4 v154, s[26:27]
	s_waitcnt vmcnt(8)
	s_waitcnt lgkmcnt(0)
	s_barrier
	s_setprio 1
	s_waitcnt lgkmcnt(0)
	v_mfma_f32_16x16x32_bf16 v[140:143], v[120:123], v[182:185], v[140:143]
	v_mfma_f32_16x16x32_bf16 v[136:139], v[128:131], v[182:185], v[136:139]
	v_mfma_f32_16x16x32_bf16 v[108:111], v[120:123], v[190:193], v[108:111]
	v_mfma_f32_16x16x32_bf16 v[104:107], v[128:131], v[190:193], v[104:107]
	v_mfma_f32_16x16x32_bf16 v[92:95], v[120:123], v[198:201], v[92:95]
	v_mfma_f32_16x16x32_bf16 v[88:91], v[128:131], v[198:201], v[88:91]
	v_mfma_f32_16x16x32_bf16 v[76:79], v[120:123], v[206:209], v[76:79]
	v_mfma_f32_16x16x32_bf16 v[72:75], v[128:131], v[206:209], v[72:75]
	v_mfma_f32_16x16x32_bf16 v[140:143], v[124:127], v[186:189], v[140:143]
	v_mfma_f32_16x16x32_bf16 v[136:139], v[132:135], v[186:189], v[136:139]
	v_mfma_f32_16x16x32_bf16 v[108:111], v[124:127], v[194:197], v[108:111]
	v_mfma_f32_16x16x32_bf16 v[104:107], v[132:135], v[194:197], v[104:107]
	v_mfma_f32_16x16x32_bf16 v[92:95], v[124:127], v[202:205], v[92:95]
	v_mfma_f32_16x16x32_bf16 v[88:91], v[132:135], v[202:205], v[88:91]
	v_mfma_f32_16x16x32_bf16 v[76:79], v[124:127], v[210:213], v[76:79]
	v_mfma_f32_16x16x32_bf16 v[72:75], v[132:135], v[210:213], v[72:75]
	s_setprio 0
	s_setprio 1
	v_mfma_f32_16x16x32_bf16 v[116:119], v[160:163], v[182:185], v[116:119]
	v_mfma_f32_16x16x32_bf16 v[112:115], v[174:177], v[182:185], v[112:115]
	v_mfma_f32_16x16x32_bf16 v[100:103], v[160:163], v[190:193], v[100:103]
	v_mfma_f32_16x16x32_bf16 v[96:99], v[174:177], v[190:193], v[96:99]
	v_mfma_f32_16x16x32_bf16 v[84:87], v[160:163], v[198:201], v[84:87]
	v_mfma_f32_16x16x32_bf16 v[80:83], v[174:177], v[198:201], v[80:83]
	v_mfma_f32_16x16x32_bf16 v[68:71], v[160:163], v[206:209], v[68:71]
	v_mfma_f32_16x16x32_bf16 v[64:67], v[174:177], v[206:209], v[64:67]
	v_mfma_f32_16x16x32_bf16 v[116:119], v[170:173], v[186:189], v[116:119]
	v_mfma_f32_16x16x32_bf16 v[112:115], v[178:181], v[186:189], v[112:115]
	v_mfma_f32_16x16x32_bf16 v[100:103], v[170:173], v[194:197], v[100:103]
	v_mfma_f32_16x16x32_bf16 v[96:99], v[178:181], v[194:197], v[96:99]
	v_mfma_f32_16x16x32_bf16 v[84:87], v[170:173], v[202:205], v[84:87]
	v_mfma_f32_16x16x32_bf16 v[80:83], v[178:181], v[202:205], v[80:83]
	v_mfma_f32_16x16x32_bf16 v[68:71], v[170:173], v[210:213], v[68:71]
	v_mfma_f32_16x16x32_bf16 v[64:67], v[178:181], v[210:213], v[64:67]
	s_setprio 0
	s_barrier
	s_add_u32 s98, s30, s12
	s_addc_u32 s99, s31, s13
	s_add_u32 s100, s34, s12
	s_addc_u32 s101, s35, s13
	s_add_i32 s26, s54, s33
	s_mov_b32 m0, s26
	ds_read_b128 v[182:185], v169 offset:16384
	ds_read_b128 v[186:189], v169 offset:17408
	ds_read_b128 v[190:193], v169 offset:18432
	ds_read_b128 v[194:197], v169 offset:19456
	ds_read_b128 v[198:201], v169 offset:20480
	ds_read_b128 v[202:205], v169 offset:21504
	ds_read_b128 v[206:209], v169 offset:22528
	ds_read_b128 v[210:213], v169 offset:23552
	global_load_lds_dwordx4 v146, s[30:31]
	s_add_i32 m0, s26, 0x2000
	s_add_u32 s26, s30, 0xb0000
	s_addc_u32 s27, s31, 0
	s_add_i32 s52, s55, s33
	global_load_lds_dwordx4 v150, s[30:31]
	s_mov_b32 m0, s52
	s_nop 0
	global_load_lds_dwordx4 v146, s[26:27]
	s_add_i32 m0, s52, 0x2000
	s_nop 0
	global_load_lds_dwordx4 v150, s[26:27]
	s_mov_b32 m0, s36
	s_nop 0
	global_load_lds_dwordx4 v144, s[34:35]
	s_mov_b32 m0, s37
	s_nop 0
	global_load_lds_dwordx4 v148, s[34:35]
	s_waitcnt vmcnt(8)
	s_waitcnt lgkmcnt(0)
	s_barrier
	s_setprio 1
	s_waitcnt lgkmcnt(0)
	v_mfma_f32_16x16x32_bf16 v[60:63], v[120:123], v[182:185], v[60:63]
	v_mfma_f32_16x16x32_bf16 v[56:59], v[128:131], v[182:185], v[56:59]
	v_mfma_f32_16x16x32_bf16 v[44:47], v[120:123], v[190:193], v[44:47]
	v_mfma_f32_16x16x32_bf16 v[40:43], v[128:131], v[190:193], v[40:43]
	v_mfma_f32_16x16x32_bf16 v[28:31], v[120:123], v[198:201], v[28:31]
	v_mfma_f32_16x16x32_bf16 v[24:27], v[128:131], v[198:201], v[24:27]
	v_mfma_f32_16x16x32_bf16 v[12:15], v[120:123], v[206:209], v[12:15]
	v_mfma_f32_16x16x32_bf16 v[8:11], v[128:131], v[206:209], v[8:11]
	v_mfma_f32_16x16x32_bf16 v[60:63], v[124:127], v[186:189], v[60:63]
	v_mfma_f32_16x16x32_bf16 v[56:59], v[132:135], v[186:189], v[56:59]
	v_mfma_f32_16x16x32_bf16 v[44:47], v[124:127], v[194:197], v[44:47]
	v_mfma_f32_16x16x32_bf16 v[40:43], v[132:135], v[194:197], v[40:43]
	v_mfma_f32_16x16x32_bf16 v[28:31], v[124:127], v[202:205], v[28:31]
	v_mfma_f32_16x16x32_bf16 v[24:27], v[132:135], v[202:205], v[24:27]
	v_mfma_f32_16x16x32_bf16 v[12:15], v[124:127], v[210:213], v[12:15]
	v_mfma_f32_16x16x32_bf16 v[8:11], v[132:135], v[210:213], v[8:11]
	s_setprio 0
	s_setprio 1
	v_mfma_f32_16x16x32_bf16 v[52:55], v[160:163], v[182:185], v[52:55]
	v_mfma_f32_16x16x32_bf16 v[48:51], v[174:177], v[182:185], v[48:51]
	v_mfma_f32_16x16x32_bf16 v[36:39], v[160:163], v[190:193], v[36:39]
	v_mfma_f32_16x16x32_bf16 v[32:35], v[174:177], v[190:193], v[32:35]
	v_mfma_f32_16x16x32_bf16 v[20:23], v[160:163], v[198:201], v[20:23]
	v_mfma_f32_16x16x32_bf16 v[16:19], v[174:177], v[198:201], v[16:19]
	v_mfma_f32_16x16x32_bf16 v[4:7], v[160:163], v[206:209], v[4:7]
	v_mfma_f32_16x16x32_bf16 v[0:3], v[174:177], v[206:209], v[0:3]
	v_mfma_f32_16x16x32_bf16 v[52:55], v[170:173], v[186:189], v[52:55]
	v_mfma_f32_16x16x32_bf16 v[48:51], v[178:181], v[186:189], v[48:51]
	v_mfma_f32_16x16x32_bf16 v[36:39], v[170:173], v[194:197], v[36:39]
	v_mfma_f32_16x16x32_bf16 v[32:35], v[178:181], v[194:197], v[32:35]
	v_mfma_f32_16x16x32_bf16 v[20:23], v[170:173], v[202:205], v[20:23]
	v_mfma_f32_16x16x32_bf16 v[16:19], v[178:181], v[202:205], v[16:19]
	v_mfma_f32_16x16x32_bf16 v[4:7], v[170:173], v[210:213], v[4:7]
	v_mfma_f32_16x16x32_bf16 v[0:3], v[178:181], v[210:213], v[0:3]
	s_setprio 0
	s_barrier
; #define PG8_STAGE(bufoff, gbase, voff) do { _Pragma("unroll") for (int _i = 0; _i < 2; ++_i) \
;         __builtin_amdgcn_global_load_lds((const unsigned*)((const char*)(gbase) + (voff)[_i]), (LAS unsigned*)(lds + (bufoff) + ldsw + _i * 8192), 16, 0, 0); } while (0)
; #define PG8_LDA(dst, b, h) do { _Pragma("unroll") for (int m = 0; m < 4; ++m) _Pragma("unroll") for (int k = 0; k < 2; ++k) dst[m][k] = *(const LAS bf16x8*)(lds + PG8_SA(b, h) + aoff + m * 2048 + k * 1024); } while (0)
; #define PG8_LDB(dst, b, h) do { _Pragma("unroll") for (int n = 0; n < 2; ++n) _Pragma("unroll") for (int k = 0; k < 2; ++k) dst[n][k] = *(const LAS bf16x8*)(lds + PG8_SB(b, h) + boff + n * 2048 + k * 1024); } while (0)
; #define PG8_MMA(ai, bj, At, Bt) do { __builtin_amdgcn_s_setprio(1); _Pragma("unroll") for (int m = 0; m < 4; ++m) _Pragma("unroll") for (int n = 0; n < 2; ++n) _Pragma("unroll") for (int k = 0; k < 2; ++k) \
;         acc[ai][bj][m][n] = __builtin_amdgcn_mfma_f32_16x16x32_bf16(Bt[n][k], At[m][k], acc[ai][bj][m][n], 0, 0, 0); __builtin_amdgcn_s_setprio(0); } while (0)
; #define PG8_WAIT_V(n) asm volatile("s_waitcnt vmcnt(" #n ")" ::: "memory")
; #define PG8_WAIT_L(n) asm volatile("s_waitcnt lgkmcnt(" #n ")" ::: "memory")
; #define PG8_BAR __builtin_amdgcn_s_barrier()
; #define PG8_SCHED __builtin_amdgcn_sched_barrier(0)
; template <class Epi, bool ALIGN_EPI, int K, int LDA, int LDB>
; __device__ __forceinline__ void gemm_phase(LAS unsigned char* lds, const int wid, const Gemm g, const StaticOrder& S, const Epi& E) {
;     ...
;             PG8_LDB(B0, 1, 0); PG8_LDB(B1, 1, 1); PG8_SCHED; PG8_LDA(At, 1, 0); PG8_STAGE(PG8_SA(0, 1), a2 + hA, voffA);
;             PG8_WAIT_V(8); PG8_WAIT_L(0); PG8_BAR; PG8_MMA(0, 0, At, B0); PG8_MMA(0, 1, At, B1); PG8_BAR; PG8_SCHED;
;             PG8_LDA(At, 1, 1); PG8_STAGE(PG8_SB(1, 0), b3, voffB); PG8_STAGE(PG8_SB(1, 1), b3 + hB, voffB); PG8_STAGE(PG8_SA(1, 0), a3, voffA);
;             PG8_WAIT_V(8); PG8_WAIT_L(0); PG8_BAR; PG8_MMA(1, 0, At, B0); PG8_MMA(1, 1, At, B1); PG8_BAR; PG8_SCHED;
;         }
;         if constexpr (ALIGN_EPI) { if (wr == 0) PG8_BAR; }
	s_add_i32 s52, 0, 0x18000
	s_add_i32 s53, 0, 0x1c000
	v_add_u32_e32 v132, s52, v166
	v_add_u32_e32 v178, s53, v166
	ds_read_b128 v[120:123], v132
	ds_read_b128 v[124:127], v132 offset:1024
	ds_read_b128 v[128:131], v132 offset:2048
	ds_read_b128 v[132:135], v132 offset:3072
	ds_read_b128 v[160:163], v178
	ds_read_b128 v[170:173], v178 offset:1024
	ds_read_b128 v[174:177], v178 offset:2048
	ds_read_b128 v[178:181], v178 offset:3072
	s_add_u32 s26, s34, 0xb0000
	s_addc_u32 s27, s35, 0
	s_mov_b32 m0, s38
	ds_read_b128 v[182:185], v169 offset:32768
	ds_read_b128 v[186:189], v169 offset:33792
	ds_read_b128 v[190:193], v169 offset:34816
	ds_read_b128 v[194:197], v169 offset:35840
	ds_read_b128 v[198:201], v169 offset:36864
	ds_read_b128 v[202:205], v169 offset:37888
	ds_read_b128 v[206:209], v169 offset:38912
	ds_read_b128 v[210:213], v169 offset:39936
	global_load_lds_dwordx4 v144, s[26:27]
	s_mov_b32 m0, s39
	s_nop 0
	global_load_lds_dwordx4 v148, s[26:27]
	s_waitcnt vmcnt(8)
	s_waitcnt lgkmcnt(0)
	s_barrier
	s_setprio 1
	s_waitcnt lgkmcnt(0)
	v_mfma_f32_16x16x32_bf16 v[140:143], v[120:123], v[182:185], v[140:143]
	v_mfma_f32_16x16x32_bf16 v[136:139], v[128:131], v[182:185], v[136:139]
	v_mfma_f32_16x16x32_bf16 v[108:111], v[120:123], v[190:193], v[108:111]
	v_mfma_f32_16x16x32_bf16 v[104:107], v[128:131], v[190:193], v[104:107]
	v_mfma_f32_16x16x32_bf16 v[92:95], v[120:123], v[198:201], v[92:95]
	v_mfma_f32_16x16x32_bf16 v[88:91], v[128:131], v[198:201], v[88:91]
	v_mfma_f32_16x16x32_bf16 v[76:79], v[120:123], v[206:209], v[76:79]
	v_mfma_f32_16x16x32_bf16 v[72:75], v[128:131], v[206:209], v[72:75]
	v_mfma_f32_16x16x32_bf16 v[140:143], v[124:127], v[186:189], v[140:143]
	v_mfma_f32_16x16x32_bf16 v[136:139], v[132:135], v[186:189], v[136:139]
	v_mfma_f32_16x16x32_bf16 v[108:111], v[124:127], v[194:197], v[108:111]
	v_mfma_f32_16x16x32_bf16 v[104:107], v[132:135], v[194:197], v[104:107]
	v_mfma_f32_16x16x32_bf16 v[92:95], v[124:127], v[202:205], v[92:95]
	v_mfma_f32_16x16x32_bf16 v[88:91], v[132:135], v[202:205], v[88:91]
	v_mfma_f32_16x16x32_bf16 v[76:79], v[124:127], v[210:213], v[76:79]
	v_mfma_f32_16x16x32_bf16 v[72:75], v[132:135], v[210:213], v[72:75]
	s_setprio 0
	s_setprio 1
	v_mfma_f32_16x16x32_bf16 v[116:119], v[160:163], v[182:185], v[116:119]
	v_mfma_f32_16x16x32_bf16 v[112:115], v[174:177], v[182:185], v[112:115]
	v_mfma_f32_16x16x32_bf16 v[100:103], v[160:163], v[190:193], v[100:103]
	v_mfma_f32_16x16x32_bf16 v[96:99], v[174:177], v[190:193], v[96:99]
	v_mfma_f32_16x16x32_bf16 v[84:87], v[160:163], v[198:201], v[84:87]
	v_mfma_f32_16x16x32_bf16 v[80:83], v[174:177], v[198:201], v[80:83]
	v_mfma_f32_16x16x32_bf16 v[68:71], v[160:163], v[206:209], v[68:71]
	v_mfma_f32_16x16x32_bf16 v[64:67], v[174:177], v[206:209], v[64:67]
	v_mfma_f32_16x16x32_bf16 v[116:119], v[170:173], v[186:189], v[116:119]
	v_mfma_f32_16x16x32_bf16 v[112:115], v[178:181], v[186:189], v[112:115]
	v_mfma_f32_16x16x32_bf16 v[100:103], v[170:173], v[194:197], v[100:103]
	v_mfma_f32_16x16x32_bf16 v[96:99], v[178:181], v[194:197], v[96:99]
	v_mfma_f32_16x16x32_bf16 v[84:87], v[170:173], v[202:205], v[84:87]
	v_mfma_f32_16x16x32_bf16 v[80:83], v[178:181], v[202:205], v[80:83]
	v_mfma_f32_16x16x32_bf16 v[68:71], v[170:173], v[210:213], v[68:71]
	v_mfma_f32_16x16x32_bf16 v[64:67], v[178:181], v[210:213], v[64:67]
	s_setprio 0
	s_barrier
	s_add_i32 s26, s52, s33
	s_mov_b32 m0, s26
	ds_read_b128 v[182:185], v169 offset:49152
	ds_read_b128 v[186:189], v169 offset:50176
	ds_read_b128 v[190:193], v169 offset:51200
	ds_read_b128 v[194:197], v169 offset:52224
	ds_read_b128 v[198:201], v169 offset:53248
	ds_read_b128 v[202:205], v169 offset:54272
	ds_read_b128 v[206:209], v169 offset:55296
	ds_read_b128 v[210:213], v169 offset:56320
	global_load_lds_dwordx4 v146, s[98:99]
	s_add_i32 m0, s26, 0x2000
	s_add_u32 s26, s30, 0xb0080
	s_addc_u32 s27, s31, 0
	s_add_i32 s30, s53, s33
	global_load_lds_dwordx4 v150, s[98:99]
	s_mov_b32 m0, s30
	s_nop 0
	global_load_lds_dwordx4 v146, s[26:27]
	s_add_i32 m0, s30, 0x2000
	s_nop 0
	global_load_lds_dwordx4 v150, s[26:27]
	s_mov_b32 m0, s48
	s_nop 0
	global_load_lds_dwordx4 v144, s[100:101]
	s_mov_b32 m0, s49
	s_nop 0
	global_load_lds_dwordx4 v148, s[100:101]
	s_waitcnt vmcnt(8)
	s_waitcnt lgkmcnt(0)
	s_barrier
	s_setprio 1
	s_waitcnt lgkmcnt(0)
	v_mfma_f32_16x16x32_bf16 v[60:63], v[120:123], v[182:185], v[60:63]
	v_mfma_f32_16x16x32_bf16 v[56:59], v[128:131], v[182:185], v[56:59]
	v_mfma_f32_16x16x32_bf16 v[44:47], v[120:123], v[190:193], v[44:47]
	v_mfma_f32_16x16x32_bf16 v[40:43], v[128:131], v[190:193], v[40:43]
	v_mfma_f32_16x16x32_bf16 v[28:31], v[120:123], v[198:201], v[28:31]
	v_mfma_f32_16x16x32_bf16 v[24:27], v[128:131], v[198:201], v[24:27]
	v_mfma_f32_16x16x32_bf16 v[12:15], v[120:123], v[206:209], v[12:15]
	v_mfma_f32_16x16x32_bf16 v[8:11], v[128:131], v[206:209], v[8:11]
	v_mfma_f32_16x16x32_bf16 v[60:63], v[124:127], v[186:189], v[60:63]
	v_mfma_f32_16x16x32_bf16 v[56:59], v[132:135], v[186:189], v[56:59]
	v_mfma_f32_16x16x32_bf16 v[44:47], v[124:127], v[194:197], v[44:47]
	v_mfma_f32_16x16x32_bf16 v[40:43], v[132:135], v[194:197], v[40:43]
	v_mfma_f32_16x16x32_bf16 v[28:31], v[124:127], v[202:205], v[28:31]
	v_mfma_f32_16x16x32_bf16 v[24:27], v[132:135], v[202:205], v[24:27]
	v_mfma_f32_16x16x32_bf16 v[12:15], v[124:127], v[210:213], v[12:15]
	v_mfma_f32_16x16x32_bf16 v[8:11], v[132:135], v[210:213], v[8:11]
	s_setprio 0
	s_setprio 1
	v_mfma_f32_16x16x32_bf16 v[52:55], v[160:163], v[182:185], v[52:55]
	v_mfma_f32_16x16x32_bf16 v[48:51], v[174:177], v[182:185], v[48:51]
	v_mfma_f32_16x16x32_bf16 v[36:39], v[160:163], v[190:193], v[36:39]
	v_mfma_f32_16x16x32_bf16 v[32:35], v[174:177], v[190:193], v[32:35]
	v_mfma_f32_16x16x32_bf16 v[20:23], v[160:163], v[198:201], v[20:23]
	v_mfma_f32_16x16x32_bf16 v[16:19], v[174:177], v[198:201], v[16:19]
	v_mfma_f32_16x16x32_bf16 v[4:7], v[160:163], v[206:209], v[4:7]
	v_mfma_f32_16x16x32_bf16 v[0:3], v[174:177], v[206:209], v[0:3]
	v_mfma_f32_16x16x32_bf16 v[52:55], v[170:173], v[186:189], v[52:55]
	v_mfma_f32_16x16x32_bf16 v[48:51], v[178:181], v[186:189], v[48:51]
	v_mfma_f32_16x16x32_bf16 v[36:39], v[170:173], v[194:197], v[36:39]
	v_mfma_f32_16x16x32_bf16 v[32:35], v[178:181], v[194:197], v[32:35]
	v_mfma_f32_16x16x32_bf16 v[20:23], v[170:173], v[202:205], v[20:23]
	v_mfma_f32_16x16x32_bf16 v[16:19], v[178:181], v[202:205], v[16:19]
	v_mfma_f32_16x16x32_bf16 v[4:7], v[170:173], v[210:213], v[4:7]
	v_mfma_f32_16x16x32_bf16 v[0:3], v[178:181], v[210:213], v[0:3]
	s_setprio 0
	s_barrier
	s_add_i32 s63, s63, 2
	s_add_u32 s61, s61, 0x100
	s_addc_u32 s62, s62, 0
	s_cmp_gt_u32 s63, 41
	s_mov_b64 s[26:27], s[28:29]
	s_cbranch_scc0 .LBB0_1697
	s_and_b64 vcc, exec, s[14:15]
	s_cbranch_vccz .LBB0_1700
	s_barrier

; __global__ void __launch_bounds__(NTHREADS) fwd_mega(Args args) {
	.amdhsa_kernel _Z8fwd_mega4Args
		.amdhsa_group_segment_fixed_size 0
		.amdhsa_private_segment_fixed_size 0
		.amdhsa_kernarg_size 536
		.amdhsa_user_sgpr_count 2
		.amdhsa_user_sgpr_dispatch_ptr 0
		.amdhsa_user_sgpr_queue_ptr 0
		.amdhsa_user_sgpr_kernarg_segment_ptr 1
		.amdhsa_user_sgpr_dispatch_id 0
		.amdhsa_user_sgpr_kernarg_preload_length 0
		.amdhsa_user_sgpr_kernarg_preload_offset 0
		.amdhsa_user_sgpr_private_segment_size 0
		.amdhsa_uses_dynamic_stack 0
		.amdhsa_enable_private_segment 0
		.amdhsa_system_sgpr_workgroup_id_x 1
		.amdhsa_system_sgpr_workgroup_id_y 0
		.amdhsa_system_sgpr_workgroup_id_z 0
		.amdhsa_system_sgpr_workgroup_info 0
		.amdhsa_system_vgpr_workitem_id 2
		.amdhsa_next_free_vgpr 255
		.amdhsa_next_free_sgpr 102
		.amdhsa_accum_offset 256
		.amdhsa_reserve_vcc 1
		.amdhsa_float_round_mode_32 0
		.amdhsa_float_round_mode_16_64 0
		.amdhsa_float_denorm_mode_32 3
		.amdhsa_float_denorm_mode_16_64 3
		.amdhsa_dx10_clamp 1
		.amdhsa_ieee_mode 1
		.amdhsa_fp16_overflow 0
		.amdhsa_tg_split 0
		.amdhsa_exception_fp_ieee_invalid_op 0
		.amdhsa_exception_fp_denorm_src 0
		.amdhsa_exception_fp_ieee_div_zero 0
		.amdhsa_exception_fp_ieee_overflow 0
		.amdhsa_exception_fp_ieee_underflow 0
		.amdhsa_exception_fp_ieee_inexact 0
		.amdhsa_exception_int_div_zero 0
	.end_amdhsa_kernel

; __global__ void __launch_bounds__(NTHREADS) fwd_mega(Args args) {
amdhsa.kernels:
  - .agpr_count:     0
    .args:
      - .offset:         0
        .size:           280
        .value_kind:     by_value
      - .offset:         280
        .size:           4
        .value_kind:     hidden_block_count_x
      - .offset:         284
        .size:           4
        .value_kind:     hidden_block_count_y
      - .offset:         288
        .size:           4
        .value_kind:     hidden_block_count_z
      - .offset:         292
        .size:           2
        .value_kind:     hidden_group_size_x
      - .offset:         294
        .size:           2
        .value_kind:     hidden_group_size_y
      - .offset:         296
        .size:           2
        .value_kind:     hidden_group_size_z
      - .offset:         298
        .size:           2
        .value_kind:     hidden_remainder_x
      - .offset:         300
        .size:           2
        .value_kind:     hidden_remainder_y
      - .offset:         302
        .size:           2
        .value_kind:     hidden_remainder_z
      - .offset:         320
        .size:           8
        .value_kind:     hidden_global_offset_x
      - .offset:         328
        .size:           8
        .value_kind:     hidden_global_offset_y
      - .offset:         336
        .size:           8
        .value_kind:     hidden_global_offset_z
      - .offset:         344
        .size:           2
        .value_kind:     hidden_grid_dims
      - .offset:         368
        .size:           8
        .value_kind:     hidden_multigrid_sync_arg
      - .offset:         400
        .size:           4
        .value_kind:     hidden_dynamic_lds_size
    .group_segment_fixed_size: 0
    .kernarg_segment_align: 8
    .kernarg_segment_size: 536
    .language:       OpenCL C
    .language_version:
      - 2
      - 0
    .max_flat_workgroup_size: 512
    .name:           _Z8fwd_mega4Args
    .private_segment_fixed_size: 0
    .sgpr_count:     108
    .sgpr_spill_count: 18
    .symbol:         _Z8fwd_mega4Args.kd
    .uniform_work_group_size: 1
    .uses_dynamic_stack: false
    .vgpr_count:     255
    .vgpr_spill_count: 0
    .wavefront_size: 64
